# out-proj GEMM epilogues (phases 5, 11): bf16 outputs regrouped by ds_bpermute so adjacent lanes store adjacent 8B pieces (64B coalesced runs)
# speedup vs baseline: 1.0085x; 1.0085x over previous
; #define PG8_STAGE(bufoff, gbase, voff) do { _Pragma("unroll") for (int _i = 0; _i < 2; ++_i) \
;         __builtin_amdgcn_global_load_lds((const unsigned*)((const char*)(gbase) + (voff)[_i]), (LAS unsigned*)(lds + (bufoff) + ldsw + _i * 8192), 16, 0, 0); } while (0)
; #define PG8_LDA(dst, b, h) do { _Pragma("unroll") for (int m = 0; m < 4; ++m) _Pragma("unroll") for (int k = 0; k < 2; ++k) dst[m][k] = *(const LAS bf16x8*)(lds + PG8_SA(b, h) + aoff + m * 2048 + k * 1024); } while (0)
; #define PG8_LDB(dst, b, h) do { _Pragma("unroll") for (int n = 0; n < 2; ++n) _Pragma("unroll") for (int k = 0; k < 2; ++k) dst[n][k] = *(const LAS bf16x8*)(lds + PG8_SB(b, h) + boff + n * 2048 + k * 1024); } while (0)
; #define PG8_MMA(ai, bj, At, Bt) do { __builtin_amdgcn_s_setprio(1); _Pragma("unroll") for (int m = 0; m < 4; ++m) _Pragma("unroll") for (int n = 0; n < 2; ++n) _Pragma("unroll") for (int k = 0; k < 2; ++k) \
;         acc[ai][bj][m][n] = __builtin_amdgcn_mfma_f32_16x16x32_bf16(Bt[n][k], At[m][k], acc[ai][bj][m][n], 0, 0, 0); __builtin_amdgcn_s_setprio(0); } while (0)
; #define PG8_WAIT_L(n) asm volatile("s_waitcnt lgkmcnt(" #n ")" ::: "memory")
; #define PG8_BAR __builtin_amdgcn_s_barrier()
; #define PG8_SCHED __builtin_amdgcn_sched_barrier(0)
; template <class Epi, class Sched>
; DI void gemm_phase(LAS unsigned char* lds, const Gemm g, const Sched& S, const Epi& E) {
;     ...
;             PG8_LDB(B0, 0, 0); PG8_SCHED; PG8_LDA(At, 0, 0); PG8_STAGE(PG8_SA(1, 1), a1 + hstep, voffA);
;             PG8_WAIT_L(8); PG8_BAR; PG8_WAIT_L(0); PG8_MMA(0, 0, At, B0); PG8_BAR; PG8_SCHED;
;             PG8_LDB(B1, 0, 1); PG8_STAGE(PG8_SB(0, 0), b2, voffB);
;             PG8_BAR; PG8_WAIT_L(0); PG8_MMA(0, 1, At, B1); PG8_BAR;
;             PG8_LDA(At, 0, 1); PG8_STAGE(PG8_SA(0, 0), a2, voffA);
;             PG8_BAR; PG8_WAIT_L(0); PG8_MMA(1, 0, At, B0); PG8_BAR; PG8_SCHED;
.LBB0_1007:
	ds_read_b128 v[140:143], v147
	ds_read_b128 v[154:157], v147 offset:1024
	ds_read_b128 v[158:161], v147 offset:2048
	ds_read_b128 v[164:167], v147 offset:3072
	s_add_u32 s24, s22, 0xfffc0080
	s_addc_u32 s25, s23, -1
	s_cmp_eq_u32 s66, 12
	s_cselect_b32 s27, s47, s25
	s_cselect_b32 s26, s53, s24
	s_cselect_b32 s25, s54, s59
	s_cselect_b32 s24, s55, s58
	s_mov_b32 m0, s36
	v_lshl_add_u64 v[150:151], s[22:23], 0, v[136:137]
	ds_read_b128 v[168:171], v148
	ds_read_b128 v[172:175], v148 offset:1024
	ds_read_b128 v[176:179], v148 offset:2048
	ds_read_b128 v[180:183], v148 offset:3072
	ds_read_b128 v[184:187], v148 offset:4096
	ds_read_b128 v[188:191], v148 offset:5120
	ds_read_b128 v[192:195], v148 offset:6144
	ds_read_b128 v[198:201], v148 offset:7168
	global_load_lds_dwordx4 v[150:151], off
	v_lshl_add_u64 v[150:151], s[22:23], 0, v[138:139]
	s_mov_b32 m0, s37
	s_nop 0
	global_load_lds_dwordx4 v[150:151], off
	s_waitcnt lgkmcnt(8)
	s_barrier
	s_waitcnt lgkmcnt(0)
	s_setprio 1
	s_waitcnt lgkmcnt(0)
	v_mfma_f32_16x16x32_bf16 v[126:129], v[140:143], v[168:171], v[126:129]
	v_mfma_f32_16x16x32_bf16 v[122:125], v[158:161], v[168:171], v[122:125]
	v_mfma_f32_16x16x32_bf16 v[114:117], v[140:143], v[176:179], v[114:117]
	v_mfma_f32_16x16x32_bf16 v[106:109], v[158:161], v[176:179], v[106:109]
	v_mfma_f32_16x16x32_bf16 v[98:101], v[140:143], v[184:187], v[98:101]
	v_mfma_f32_16x16x32_bf16 v[90:93], v[158:161], v[184:187], v[90:93]
	v_mfma_f32_16x16x32_bf16 v[82:85], v[140:143], v[192:195], v[82:85]
	v_mfma_f32_16x16x32_bf16 v[74:77], v[158:161], v[192:195], v[74:77]
	v_mfma_f32_16x16x32_bf16 v[126:129], v[154:157], v[172:175], v[126:129]
	v_mfma_f32_16x16x32_bf16 v[122:125], v[164:167], v[172:175], v[122:125]
	v_mfma_f32_16x16x32_bf16 v[114:117], v[154:157], v[180:183], v[114:117]
	v_mfma_f32_16x16x32_bf16 v[106:109], v[164:167], v[180:183], v[106:109]
	v_mfma_f32_16x16x32_bf16 v[98:101], v[154:157], v[188:191], v[98:101]
	v_mfma_f32_16x16x32_bf16 v[90:93], v[164:167], v[188:191], v[90:93]
	v_mfma_f32_16x16x32_bf16 v[82:85], v[154:157], v[198:201], v[82:85]
	v_mfma_f32_16x16x32_bf16 v[74:77], v[164:167], v[198:201], v[74:77]
	s_setprio 0
	s_barrier
	s_mov_b32 m0, s38
	v_lshl_add_u64 v[150:151], s[24:25], 0, v[132:133]
	ds_read_b128 v[202:205], v149
	ds_read_b128 v[206:209], v149 offset:1024
	ds_read_b128 v[210:213], v149 offset:2048
	ds_read_b128 v[214:217], v149 offset:3072
	global_load_lds_dwordx4 v[150:151], off
	v_lshl_add_u64 v[218:219], s[24:25], 0, v[130:131]
	s_mov_b32 m0, s39
	s_nop 0
	global_load_lds_dwordx4 v[218:219], off
	s_barrier
	s_waitcnt lgkmcnt(0)
	s_setprio 1
	s_waitcnt lgkmcnt(0)
	v_mfma_f32_16x16x32_bf16 v[118:121], v[202:205], v[168:171], v[118:121]
	v_mfma_f32_16x16x32_bf16 v[110:113], v[210:213], v[168:171], v[110:113]
	v_mfma_f32_16x16x32_bf16 v[102:105], v[202:205], v[176:179], v[102:105]
	v_mfma_f32_16x16x32_bf16 v[94:97], v[210:213], v[176:179], v[94:97]
	v_mfma_f32_16x16x32_bf16 v[86:89], v[202:205], v[184:187], v[86:89]
	v_mfma_f32_16x16x32_bf16 v[78:81], v[210:213], v[184:187], v[78:81]
	v_mfma_f32_16x16x32_bf16 v[70:73], v[202:205], v[192:195], v[70:73]
	v_mfma_f32_16x16x32_bf16 v[66:69], v[210:213], v[192:195], v[66:69]
	v_mfma_f32_16x16x32_bf16 v[118:121], v[206:209], v[172:175], v[118:121]
	v_mfma_f32_16x16x32_bf16 v[110:113], v[214:217], v[172:175], v[110:113]
	v_mfma_f32_16x16x32_bf16 v[102:105], v[206:209], v[180:183], v[102:105]
	v_mfma_f32_16x16x32_bf16 v[94:97], v[214:217], v[180:183], v[94:97]
	v_mfma_f32_16x16x32_bf16 v[86:89], v[206:209], v[188:191], v[86:89]
	v_mfma_f32_16x16x32_bf16 v[78:81], v[214:217], v[188:191], v[78:81]
	v_mfma_f32_16x16x32_bf16 v[70:73], v[206:209], v[198:201], v[70:73]
	v_mfma_f32_16x16x32_bf16 v[66:69], v[214:217], v[198:201], v[66:69]
	s_setprio 0
	s_mov_b32 m0, s13
	v_lshl_add_u64 v[220:221], s[26:27], 0, v[132:133]
	s_barrier
	ds_read_b128 v[168:171], v148 offset:16384
	ds_read_b128 v[172:175], v148 offset:17408
	ds_read_b128 v[176:179], v148 offset:18432
	ds_read_b128 v[180:183], v148 offset:19456
	ds_read_b128 v[184:187], v148 offset:20480
	ds_read_b128 v[188:191], v148 offset:21504
	ds_read_b128 v[192:195], v148 offset:22528
	ds_read_b128 v[198:201], v148 offset:23552
	global_load_lds_dwordx4 v[220:221], off
	v_lshl_add_u64 v[222:223], s[26:27], 0, v[130:131]
	s_mov_b32 m0, s28
	s_nop 0
	global_load_lds_dwordx4 v[222:223], off
	s_barrier
	s_waitcnt lgkmcnt(0)
	s_setprio 1
	s_waitcnt lgkmcnt(0)
	v_mfma_f32_16x16x32_bf16 v[62:65], v[140:143], v[168:171], v[62:65]
	v_mfma_f32_16x16x32_bf16 v[58:61], v[158:161], v[168:171], v[58:61]
	v_mfma_f32_16x16x32_bf16 v[50:53], v[140:143], v[176:179], v[50:53]
	v_mfma_f32_16x16x32_bf16 v[42:45], v[158:161], v[176:179], v[42:45]
	v_mfma_f32_16x16x32_bf16 v[34:37], v[140:143], v[184:187], v[34:37]
	v_mfma_f32_16x16x32_bf16 v[26:29], v[158:161], v[184:187], v[26:29]
	v_mfma_f32_16x16x32_bf16 v[18:21], v[140:143], v[192:195], v[18:21]
	v_mfma_f32_16x16x32_bf16 v[10:13], v[158:161], v[192:195], v[10:13]
	v_mfma_f32_16x16x32_bf16 v[62:65], v[154:157], v[172:175], v[62:65]
	v_mfma_f32_16x16x32_bf16 v[58:61], v[164:167], v[172:175], v[58:61]
	v_mfma_f32_16x16x32_bf16 v[50:53], v[154:157], v[180:183], v[50:53]
	v_mfma_f32_16x16x32_bf16 v[42:45], v[164:167], v[180:183], v[42:45]
	v_mfma_f32_16x16x32_bf16 v[34:37], v[154:157], v[188:191], v[34:37]
	v_mfma_f32_16x16x32_bf16 v[26:29], v[164:167], v[188:191], v[26:29]
	v_mfma_f32_16x16x32_bf16 v[18:21], v[154:157], v[198:201], v[18:21]
	v_mfma_f32_16x16x32_bf16 v[10:13], v[164:167], v[198:201], v[10:13]
	s_setprio 0
	s_barrier
; #define PG8_STAGE(bufoff, gbase, voff) do { _Pragma("unroll") for (int _i = 0; _i < 2; ++_i) \
;         __builtin_amdgcn_global_load_lds((const unsigned*)((const char*)(gbase) + (voff)[_i]), (LAS unsigned*)(lds + (bufoff) + ldsw + _i * 8192), 16, 0, 0); } while (0)
; #define PG8_LDA(dst, b, h) do { _Pragma("unroll") for (int m = 0; m < 4; ++m) _Pragma("unroll") for (int k = 0; k < 2; ++k) dst[m][k] = *(const LAS bf16x8*)(lds + PG8_SA(b, h) + aoff + m * 2048 + k * 1024); } while (0)
; #define PG8_LDB(dst, b, h) do { _Pragma("unroll") for (int n = 0; n < 2; ++n) _Pragma("unroll") for (int k = 0; k < 2; ++k) dst[n][k] = *(const LAS bf16x8*)(lds + PG8_SB(b, h) + boff + n * 2048 + k * 1024); } while (0)
; #define PG8_MMA(ai, bj, At, Bt) do { __builtin_amdgcn_s_setprio(1); _Pragma("unroll") for (int m = 0; m < 4; ++m) _Pragma("unroll") for (int n = 0; n < 2; ++n) _Pragma("unroll") for (int k = 0; k < 2; ++k) \
;         acc[ai][bj][m][n] = __builtin_amdgcn_mfma_f32_16x16x32_bf16(Bt[n][k], At[m][k], acc[ai][bj][m][n], 0, 0, 0); __builtin_amdgcn_s_setprio(0); } while (0)
; #define PG8_WAIT_V(n) asm volatile("s_waitcnt vmcnt(" #n ")" ::: "memory")
; #define PG8_WAIT_L(n) asm volatile("s_waitcnt lgkmcnt(" #n ")" ::: "memory")
; #define PG8_BAR __builtin_amdgcn_s_barrier()
; #define PG8_SCHED __builtin_amdgcn_sched_barrier(0)
; template <class Epi, class Sched>
; DI void gemm_phase(LAS unsigned char* lds, const Gemm g, const Sched& S, const Epi& E) {
;     ...
;             PG8_STAGE(PG8_SB(0, 1), b2 + hstep, voffB);
;             PG8_WAIT_V(6); PG8_BAR; PG8_MMA(1, 1, At, B1); PG8_BAR;
;             PG8_LDB(B0, 1, 0); PG8_SCHED; PG8_LDA(At, 1, 0); PG8_STAGE(PG8_SA(0, 1), a2 + hstep, voffA);
;             PG8_WAIT_L(8); PG8_BAR; PG8_WAIT_L(0); PG8_MMA(0, 0, At, B0); PG8_BAR; PG8_SCHED;
;             PG8_LDB(B1, 1, 1); PG8_STAGE(PG8_SB(1, 0), b3, voffB);
;             PG8_BAR; PG8_WAIT_L(0); PG8_MMA(0, 1, At, B1); PG8_BAR;
;             PG8_LDA(At, 1, 1); PG8_STAGE(PG8_SA(1, 0), a3, voffA);
;             PG8_BAR; PG8_WAIT_L(0); PG8_MMA(1, 0, At, B0); PG8_BAR; PG8_SCHED;
	s_add_u32 s72, s24, 0x40000
	s_addc_u32 s73, s25, 0
	s_add_i32 s67, s35, s12
	v_lshl_add_u64 v[140:141], s[72:73], 0, v[132:133]
	s_mov_b32 m0, s67
	s_nop 0
	global_load_lds_dwordx4 v[140:141], off
	v_lshl_add_u64 v[140:141], s[72:73], 0, v[130:131]
	s_add_i32 m0, s67, 0x2000
	s_nop 0
	global_load_lds_dwordx4 v[140:141], off
	s_waitcnt vmcnt(6)
	s_barrier
	s_setprio 1
	v_mfma_f32_16x16x32_bf16 v[54:57], v[202:205], v[168:171], v[54:57]
	v_mfma_f32_16x16x32_bf16 v[46:49], v[210:213], v[168:171], v[46:49]
	v_mfma_f32_16x16x32_bf16 v[38:41], v[202:205], v[176:179], v[38:41]
	v_mfma_f32_16x16x32_bf16 v[30:33], v[210:213], v[176:179], v[30:33]
	v_mfma_f32_16x16x32_bf16 v[22:25], v[202:205], v[184:187], v[22:25]
	v_mfma_f32_16x16x32_bf16 v[14:17], v[210:213], v[184:187], v[14:17]
	v_mfma_f32_16x16x32_bf16 v[6:9], v[202:205], v[192:195], v[6:9]
	v_mfma_f32_16x16x32_bf16 v[2:5], v[210:213], v[192:195], v[2:5]
	v_mfma_f32_16x16x32_bf16 v[54:57], v[206:209], v[172:175], v[54:57]
	v_mfma_f32_16x16x32_bf16 v[46:49], v[214:217], v[172:175], v[46:49]
	v_mfma_f32_16x16x32_bf16 v[38:41], v[206:209], v[180:183], v[38:41]
	v_mfma_f32_16x16x32_bf16 v[30:33], v[214:217], v[180:183], v[30:33]
	v_mfma_f32_16x16x32_bf16 v[22:25], v[206:209], v[188:191], v[22:25]
	v_mfma_f32_16x16x32_bf16 v[14:17], v[214:217], v[188:191], v[14:17]
	v_mfma_f32_16x16x32_bf16 v[6:9], v[206:209], v[198:201], v[6:9]
	v_mfma_f32_16x16x32_bf16 v[2:5], v[214:217], v[198:201], v[2:5]
	s_setprio 0
	s_add_i32 s67, 0, 0x18000
	v_add_u32_e32 v134, s67, v145
	s_barrier
	ds_read_b128 v[140:143], v134
	ds_read_b128 v[154:157], v134 offset:1024
	ds_read_b128 v[158:161], v134 offset:2048
	ds_read_b128 v[164:167], v134 offset:3072
	s_add_u32 s26, s26, 0x40000
	s_addc_u32 s27, s27, 0
	s_mov_b32 m0, s29
	v_lshl_add_u64 v[202:203], s[26:27], 0, v[132:133]
	ds_read_b128 v[168:171], v148 offset:32768
	ds_read_b128 v[172:175], v148 offset:33792
	ds_read_b128 v[176:179], v148 offset:34816
	ds_read_b128 v[180:183], v148 offset:35840
	ds_read_b128 v[184:187], v148 offset:36864
	ds_read_b128 v[188:191], v148 offset:37888
	ds_read_b128 v[192:195], v148 offset:38912
	ds_read_b128 v[198:201], v148 offset:39936
	global_load_lds_dwordx4 v[202:203], off
	v_lshl_add_u64 v[202:203], s[26:27], 0, v[130:131]
	s_mov_b32 m0, s30
	s_nop 0
	global_load_lds_dwordx4 v[202:203], off
	s_waitcnt lgkmcnt(8)
	s_barrier
	s_waitcnt lgkmcnt(0)
	s_setprio 1
	s_waitcnt lgkmcnt(0)
	v_mfma_f32_16x16x32_bf16 v[126:129], v[140:143], v[168:171], v[126:129]
	v_mfma_f32_16x16x32_bf16 v[122:125], v[158:161], v[168:171], v[122:125]
	v_mfma_f32_16x16x32_bf16 v[114:117], v[140:143], v[176:179], v[114:117]
	v_mfma_f32_16x16x32_bf16 v[106:109], v[158:161], v[176:179], v[106:109]
	v_mfma_f32_16x16x32_bf16 v[98:101], v[140:143], v[184:187], v[98:101]
	v_mfma_f32_16x16x32_bf16 v[90:93], v[158:161], v[184:187], v[90:93]
	v_mfma_f32_16x16x32_bf16 v[82:85], v[140:143], v[192:195], v[82:85]
	v_mfma_f32_16x16x32_bf16 v[74:77], v[158:161], v[192:195], v[74:77]
	v_mfma_f32_16x16x32_bf16 v[126:129], v[154:157], v[172:175], v[126:129]
	v_mfma_f32_16x16x32_bf16 v[122:125], v[164:167], v[172:175], v[122:125]
	v_mfma_f32_16x16x32_bf16 v[114:117], v[154:157], v[180:183], v[114:117]
	v_mfma_f32_16x16x32_bf16 v[106:109], v[164:167], v[180:183], v[106:109]
	v_mfma_f32_16x16x32_bf16 v[98:101], v[154:157], v[188:191], v[98:101]
	v_mfma_f32_16x16x32_bf16 v[90:93], v[164:167], v[188:191], v[90:93]
	v_mfma_f32_16x16x32_bf16 v[82:85], v[154:157], v[198:201], v[82:85]
	v_mfma_f32_16x16x32_bf16 v[74:77], v[164:167], v[198:201], v[74:77]
	s_setprio 0
	s_barrier
	s_add_i32 s26, 0, 0x1c000
	s_add_i32 s27, s67, s12
	v_add_u32_e32 v134, s26, v145
	v_lshl_add_u64 v[150:151], v[150:151], 0, s[10:11]
	s_mov_b32 m0, s27
	ds_read_b128 v[202:205], v134
	ds_read_b128 v[206:209], v134 offset:1024
	ds_read_b128 v[210:213], v134 offset:2048
	ds_read_b128 v[214:217], v134 offset:3072
	global_load_lds_dwordx4 v[150:151], off
	v_lshl_add_u64 v[150:151], v[218:219], 0, s[10:11]
	s_add_i32 m0, s27, 0x2000
	s_nop 0
	global_load_lds_dwordx4 v[150:151], off
	s_barrier
	s_waitcnt lgkmcnt(0)
	s_setprio 1
	s_waitcnt lgkmcnt(0)
	v_mfma_f32_16x16x32_bf16 v[118:121], v[202:205], v[168:171], v[118:121]
	v_mfma_f32_16x16x32_bf16 v[110:113], v[210:213], v[168:171], v[110:113]
	v_mfma_f32_16x16x32_bf16 v[102:105], v[202:205], v[176:179], v[102:105]
	v_mfma_f32_16x16x32_bf16 v[94:97], v[210:213], v[176:179], v[94:97]
	v_mfma_f32_16x16x32_bf16 v[86:89], v[202:205], v[184:187], v[86:89]
	v_mfma_f32_16x16x32_bf16 v[78:81], v[210:213], v[184:187], v[78:81]
	v_mfma_f32_16x16x32_bf16 v[70:73], v[202:205], v[192:195], v[70:73]
	v_mfma_f32_16x16x32_bf16 v[66:69], v[210:213], v[192:195], v[66:69]
	v_mfma_f32_16x16x32_bf16 v[118:121], v[206:209], v[172:175], v[118:121]
	v_mfma_f32_16x16x32_bf16 v[110:113], v[214:217], v[172:175], v[110:113]
	v_mfma_f32_16x16x32_bf16 v[102:105], v[206:209], v[180:183], v[102:105]
	v_mfma_f32_16x16x32_bf16 v[94:97], v[214:217], v[180:183], v[94:97]
	v_mfma_f32_16x16x32_bf16 v[86:89], v[206:209], v[188:191], v[86:89]
	v_mfma_f32_16x16x32_bf16 v[78:81], v[214:217], v[188:191], v[78:81]
	v_mfma_f32_16x16x32_bf16 v[70:73], v[206:209], v[198:201], v[70:73]
	v_mfma_f32_16x16x32_bf16 v[66:69], v[214:217], v[198:201], v[66:69]
	s_setprio 0
	s_mov_b32 m0, s33
	v_lshl_add_u64 v[150:151], v[220:221], 0, s[10:11]
	s_barrier
	ds_read_b128 v[168:171], v148 offset:49152
	ds_read_b128 v[172:175], v148 offset:50176
	ds_read_b128 v[176:179], v148 offset:51200
	ds_read_b128 v[180:183], v148 offset:52224
	ds_read_b128 v[184:187], v148 offset:53248
	ds_read_b128 v[188:191], v148 offset:54272
	ds_read_b128 v[192:195], v148 offset:55296
	ds_read_b128 v[198:201], v148 offset:56320
	global_load_lds_dwordx4 v[150:151], off
	v_lshl_add_u64 v[150:151], v[222:223], 0, s[10:11]
	s_mov_b32 m0, s34
	s_nop 0
	global_load_lds_dwordx4 v[150:151], off
	s_barrier
; #define PG8_STAGE(bufoff, gbase, voff) do { _Pragma("unroll") for (int _i = 0; _i < 2; ++_i) \
;         __builtin_amdgcn_global_load_lds((const unsigned*)((const char*)(gbase) + (voff)[_i]), (LAS unsigned*)(lds + (bufoff) + ldsw + _i * 8192), 16, 0, 0); } while (0)
; #define PG8_MMA(ai, bj, At, Bt) do { __builtin_amdgcn_s_setprio(1); _Pragma("unroll") for (int m = 0; m < 4; ++m) _Pragma("unroll") for (int n = 0; n < 2; ++n) _Pragma("unroll") for (int k = 0; k < 2; ++k) \
;         acc[ai][bj][m][n] = __builtin_amdgcn_mfma_f32_16x16x32_bf16(Bt[n][k], At[m][k], acc[ai][bj][m][n], 0, 0, 0); __builtin_amdgcn_s_setprio(0); } while (0)
; #define PG8_WAIT_V(n) asm volatile("s_waitcnt vmcnt(" #n ")" ::: "memory")
; #define PG8_WAIT_L(n) asm volatile("s_waitcnt lgkmcnt(" #n ")" ::: "memory")
; #define PG8_BAR __builtin_amdgcn_s_barrier()
; #define PG8_SCHED __builtin_amdgcn_sched_barrier(0)
;     DI void operator()(const f32x4 (&acc)[2][2][4][2], const Unit& u, int wr, int wc, int fr, int fq) const {
;         const int row0 = u.pm * BM + wr * 64 + fr, col0 = u.pn * BM + wc * 32 + 4 * fq;
; #pragma unroll
;         for (int ai = 0; ai < 2; ++ai)
; #pragma unroll
;             for (int m = 0; m < 4; ++m) { const size_t o = (size_t)(row0 + ai * HALF + m * 16) * 1024 + col0;
; template <class Epi, class Sched>
; DI void gemm_phase(LAS unsigned char* lds, const Gemm g, const Sched& S, const Epi& E) {
;     ...
;             PG8_BAR; PG8_WAIT_L(0); PG8_MMA(1, 0, At, B0); PG8_BAR; PG8_SCHED;
;             PG8_STAGE(PG8_SB(1, 1), b3 + hstep, voffB);
;             PG8_WAIT_V(6); PG8_BAR; PG8_MMA(1, 1, At, B1); PG8_BAR;
	s_waitcnt lgkmcnt(0)
	s_setprio 1
	s_waitcnt lgkmcnt(0)
	v_mfma_f32_16x16x32_bf16 v[62:65], v[140:143], v[168:171], v[62:65]
	v_mfma_f32_16x16x32_bf16 v[58:61], v[158:161], v[168:171], v[58:61]
	v_mfma_f32_16x16x32_bf16 v[50:53], v[140:143], v[176:179], v[50:53]
	v_mfma_f32_16x16x32_bf16 v[42:45], v[158:161], v[176:179], v[42:45]
	v_mfma_f32_16x16x32_bf16 v[34:37], v[140:143], v[184:187], v[34:37]
	v_mfma_f32_16x16x32_bf16 v[26:29], v[158:161], v[184:187], v[26:29]
	v_mfma_f32_16x16x32_bf16 v[18:21], v[140:143], v[192:195], v[18:21]
	v_mfma_f32_16x16x32_bf16 v[10:13], v[158:161], v[192:195], v[10:13]
	v_mfma_f32_16x16x32_bf16 v[62:65], v[154:157], v[172:175], v[62:65]
	v_mfma_f32_16x16x32_bf16 v[58:61], v[164:167], v[172:175], v[58:61]
	v_mfma_f32_16x16x32_bf16 v[50:53], v[154:157], v[180:183], v[50:53]
	v_mfma_f32_16x16x32_bf16 v[42:45], v[164:167], v[180:183], v[42:45]
	v_mfma_f32_16x16x32_bf16 v[34:37], v[154:157], v[188:191], v[34:37]
	v_mfma_f32_16x16x32_bf16 v[26:29], v[164:167], v[188:191], v[26:29]
	v_mfma_f32_16x16x32_bf16 v[18:21], v[154:157], v[198:201], v[18:21]
	v_mfma_f32_16x16x32_bf16 v[10:13], v[164:167], v[198:201], v[10:13]
	s_setprio 0
	s_barrier
	s_add_u32 s24, s24, 0x40080
	s_addc_u32 s25, s25, 0
	s_add_i32 s26, s26, s12
	v_lshl_add_u64 v[140:141], s[24:25], 0, v[132:133]
	s_mov_b32 m0, s26
	s_nop 0
	global_load_lds_dwordx4 v[140:141], off
	v_lshl_add_u64 v[140:141], s[24:25], 0, v[130:131]
	s_add_i32 m0, s26, 0x2000
	s_nop 0
	global_load_lds_dwordx4 v[140:141], off
	s_waitcnt vmcnt(6)
	s_barrier
	s_setprio 1
	v_mfma_f32_16x16x32_bf16 v[54:57], v[202:205], v[168:171], v[54:57]
	v_mfma_f32_16x16x32_bf16 v[46:49], v[210:213], v[168:171], v[46:49]
	v_mfma_f32_16x16x32_bf16 v[38:41], v[202:205], v[176:179], v[38:41]
	v_mfma_f32_16x16x32_bf16 v[30:33], v[210:213], v[176:179], v[30:33]
	v_mfma_f32_16x16x32_bf16 v[22:25], v[202:205], v[184:187], v[22:25]
	v_mfma_f32_16x16x32_bf16 v[14:17], v[210:213], v[184:187], v[14:17]
	v_mfma_f32_16x16x32_bf16 v[6:9], v[202:205], v[192:195], v[6:9]
	v_mfma_f32_16x16x32_bf16 v[2:5], v[210:213], v[192:195], v[2:5]
	v_mfma_f32_16x16x32_bf16 v[54:57], v[206:209], v[172:175], v[54:57]
	v_mfma_f32_16x16x32_bf16 v[46:49], v[214:217], v[172:175], v[46:49]
	v_mfma_f32_16x16x32_bf16 v[38:41], v[206:209], v[180:183], v[38:41]
	v_mfma_f32_16x16x32_bf16 v[30:33], v[214:217], v[180:183], v[30:33]
	v_mfma_f32_16x16x32_bf16 v[22:25], v[206:209], v[188:191], v[22:25]
	v_mfma_f32_16x16x32_bf16 v[14:17], v[214:217], v[188:191], v[14:17]
	v_mfma_f32_16x16x32_bf16 v[6:9], v[206:209], v[198:201], v[6:9]
	v_mfma_f32_16x16x32_bf16 v[2:5], v[214:217], v[198:201], v[2:5]
	s_setprio 0
	s_add_i32 s66, s66, 2
	s_add_u32 s22, s22, 0x100
	s_addc_u32 s23, s23, 0
	s_add_u32 s58, s58, 0x100
	s_addc_u32 s59, s59, 0
	s_cmp_gt_u32 s66, 13
	s_barrier
	s_cbranch_scc0 .LBB0_1007
	v_lshl_add_u32 v224, s43, 8, v144
	v_lshl_or_b32 v243, s42, 8, v146
	v_lshl_or_b32 v224, v224, 10, v243
	v_lshlrev_b32_e32 v225, 2, v224
	v_lshlrev_b32_e32 v233, 1, v224
	v_add_u32_e32 v234, 0x4000, v224
	v_lshlrev_b32_e32 v226, 2, v234
	v_lshlrev_b32_e32 v234, 1, v234
	v_add_u32_e32 v235, 0x8000, v224
	v_lshlrev_b32_e32 v227, 2, v235
	v_lshlrev_b32_e32 v235, 1, v235
	v_add_u32_e32 v236, 0xc000, v224
	v_lshlrev_b32_e32 v228, 2, v236
	v_lshlrev_b32_e32 v236, 1, v236
	v_add_u32_e32 v237, 0x20000, v224
	v_lshlrev_b32_e32 v229, 2, v237
	v_lshlrev_b32_e32 v237, 1, v237
	v_add_u32_e32 v240, 0x24000, v224
	v_lshlrev_b32_e32 v230, 2, v240
	v_lshlrev_b32_e32 v240, 1, v240
	v_add_u32_e32 v241, 0x28000, v224
	v_lshlrev_b32_e32 v231, 2, v241
	v_lshlrev_b32_e32 v241, 1, v241
	v_add_u32_e32 v242, 0x2c000, v224
	v_lshlrev_b32_e32 v232, 2, v242
	v_lshlrev_b32_e32 v242, 1, v242
	v_and_b32_e32 v248, 63, v1
	v_lshrrev_b32_e32 v249, 3, v248
	v_and_b32_e32 v250, 3, v248
	v_lshl_or_b32 v250, v250, 4, v249
	v_lshlrev_b32_e32 v244, 2, v250
	v_add_u32_e32 v245, 32, v244
	v_and_b32_e32 v250, 0xffffffc0, v144
	v_add_u32_e32 v250, v250, v249
	v_lshl_add_u32 v250, s43, 8, v250
	v_mul_u32_u24_e32 v250, 0x800, v250
	v_and_b32_e32 v247, 0xffffffe0, v146
	v_lshl_or_b32 v247, s42, 8, v247
	v_lshlrev_b32_e32 v247, 1, v247
	v_and_b32_e32 v248, 7, v248
	v_lshl_add_u32 v247, v248, 3, v247
	v_add_u32_e32 v246, v250, v247
	s_mov_b32 s98, 0xf0f0f0f0
	s_mov_b32 s99, 0xf0f0f0f0
	s_and_b64 vcc, exec, s[20:21]
	s_mov_b32 s42, s40
	s_mov_b32 s43, s41
	s_mov_b64 s[22:23], 0x2c000
	global_load_dwordx4 v[140:143], v225, s[60:61]
	global_load_dwordx4 v[154:157], v225, s[60:61] offset:64
	global_load_dwordx4 v[158:161], v225, s[60:61] offset:512
	global_load_dwordx4 v[164:167], v225, s[60:61] offset:576
	global_load_dwordx4 v[168:171], v226, s[60:61]
	global_load_dwordx4 v[172:175], v226, s[60:61] offset:64
	global_load_dwordx4 v[176:179], v226, s[60:61] offset:512
	global_load_dwordx4 v[180:183], v226, s[60:61] offset:576
	global_load_dwordx4 v[184:187], v227, s[60:61]
	global_load_dwordx4 v[188:191], v227, s[60:61] offset:64
	global_load_dwordx4 v[192:195], v227, s[60:61] offset:512
	global_load_dwordx4 v[198:201], v227, s[60:61] offset:576
	global_load_dwordx4 v[202:205], v228, s[60:61]
	global_load_dwordx4 v[206:209], v228, s[60:61] offset:64
	global_load_dwordx4 v[210:213], v228, s[60:61] offset:512
	global_load_dwordx4 v[214:217], v228, s[60:61] offset:576
	s_waitcnt vmcnt(12)
; DI unsigned pk_bf16(float a, float b) { f32x2 v = {a, b}; bf2_t r = __builtin_convertvector(v, bf2_t); return __builtin_bit_cast(unsigned, r); }
; DI float bflo(unsigned u) { return __uint_as_float(u << 16); }
; DI float bfhi(unsigned u) { return __uint_as_float(u & 0xffff0000u); }
;     DI void operator()(const f32x4 (&acc)[2][2][4][2], const Unit& u, int wr, int wc, int fr, int fq) const {
;     ...
;             for (int m = 0; m < 4; ++m) { const size_t o = (size_t)(row0 + ai * HALF + m * 16) * 1024 + col0;
; #pragma unroll
;                 for (int bj = 0; bj < 2; ++bj)
; #pragma unroll
;                     for (int n = 0; n < 2; ++n) { const size_t oo = o + bj * HALF + n * 16; f32x4 rv;
;                         if (RES_BF16) { const u32x2 t = *(const u32x2*)((const bf16_t*)res + oo); rv = (f32x4){bflo(t.x), bfhi(t.x), bflo(t.y), bfhi(t.y)}; }
;                         else rv = *(const f32x4*)((const float*)res + oo);
;                         const f32x4 v = acc[ai][bj][m][n] + rv; u32x2 w; w.x = pk_bf16(v.x, v.y); w.y = pk_bf16(v.z, v.w);
;                         *(u32x2*)(O + oo) = w; } }
	v_pk_add_f32 v[128:129], v[128:129], v[142:143]
	v_pk_add_f32 v[126:127], v[126:127], v[140:141]
	v_pk_add_f32 v[124:125], v[124:125], v[156:157]
	v_pk_add_f32 v[122:123], v[122:123], v[154:155]
	v_pk_add_f32 v[120:121], v[120:121], v[160:161]
	v_pk_add_f32 v[118:119], v[118:119], v[158:159]
	v_pk_add_f32 v[112:113], v[112:113], v[166:167]
	v_pk_add_f32 v[110:111], v[110:111], v[164:165]
	v_cvt_pk_bf16_f32 v126, v126, v127
	v_cvt_pk_bf16_f32 v127, v128, v129
	v_cvt_pk_bf16_f32 v122, v122, v123
	v_cvt_pk_bf16_f32 v123, v124, v125
	v_cvt_pk_bf16_f32 v118, v118, v119
	v_cvt_pk_bf16_f32 v119, v120, v121
	v_cvt_pk_bf16_f32 v110, v110, v111
	v_cvt_pk_bf16_f32 v111, v112, v113
	ds_bpermute_b32 v140, v244, v126
	ds_bpermute_b32 v141, v244, v127
	ds_bpermute_b32 v142, v244, v122
	ds_bpermute_b32 v143, v244, v123
	ds_bpermute_b32 v154, v245, v126
	ds_bpermute_b32 v155, v245, v127
	ds_bpermute_b32 v156, v245, v122
	ds_bpermute_b32 v157, v245, v123
	s_waitcnt lgkmcnt(0)
	v_cndmask_b32_e64 v140, v140, v142, s[98:99]
	v_cndmask_b32_e64 v141, v141, v143, s[98:99]
	v_mov_b32_e32 v142, v246
	global_store_dwordx2 v142, v[140:141], s[48:49]
	v_cndmask_b32_e64 v154, v154, v156, s[98:99]
	v_cndmask_b32_e64 v155, v155, v157, s[98:99]
	v_add_u32_e32 v156, 0x4000, v246
	global_store_dwordx2 v156, v[154:155], s[48:49]
	ds_bpermute_b32 v140, v244, v118
	ds_bpermute_b32 v141, v244, v119
	ds_bpermute_b32 v142, v244, v110
	ds_bpermute_b32 v143, v244, v111
	ds_bpermute_b32 v154, v245, v118
	ds_bpermute_b32 v155, v245, v119
	ds_bpermute_b32 v156, v245, v110
	ds_bpermute_b32 v157, v245, v111
	s_waitcnt lgkmcnt(0)
	v_cndmask_b32_e64 v140, v140, v142, s[98:99]
	v_cndmask_b32_e64 v141, v141, v143, s[98:99]
	v_mov_b32_e32 v142, v246
	global_store_dwordx2 v142, v[140:141], s[48:49] offset:256
	v_cndmask_b32_e64 v154, v154, v156, s[98:99]
	v_cndmask_b32_e64 v155, v155, v157, s[98:99]
	v_add_u32_e32 v156, 0x4000, v246
	global_store_dwordx2 v156, v[154:155], s[48:49] offset:256
	global_load_dwordx4 v[140:143], v229, s[60:61]
	global_load_dwordx4 v[154:157], v229, s[60:61] offset:64
	global_load_dwordx4 v[158:161], v229, s[60:61] offset:512
	global_load_dwordx4 v[164:167], v229, s[60:61] offset:576
	s_waitcnt vmcnt(16)
	v_pk_add_f32 v[116:117], v[116:117], v[170:171]
	v_pk_add_f32 v[114:115], v[114:115], v[168:169]
	v_pk_add_f32 v[108:109], v[108:109], v[174:175]
	v_pk_add_f32 v[106:107], v[106:107], v[172:173]
	v_pk_add_f32 v[104:105], v[104:105], v[178:179]
	v_pk_add_f32 v[102:103], v[102:103], v[176:177]
	v_pk_add_f32 v[96:97], v[96:97], v[182:183]
	v_pk_add_f32 v[94:95], v[94:95], v[180:181]
	v_cvt_pk_bf16_f32 v114, v114, v115
	v_cvt_pk_bf16_f32 v115, v116, v117
	v_cvt_pk_bf16_f32 v106, v106, v107
	v_cvt_pk_bf16_f32 v107, v108, v109
	v_cvt_pk_bf16_f32 v102, v102, v103
	v_cvt_pk_bf16_f32 v103, v104, v105
	v_cvt_pk_bf16_f32 v94, v94, v95
	v_cvt_pk_bf16_f32 v95, v96, v97
	ds_bpermute_b32 v168, v244, v114
	ds_bpermute_b32 v169, v244, v115
	ds_bpermute_b32 v170, v244, v106
	ds_bpermute_b32 v171, v244, v107
	ds_bpermute_b32 v172, v245, v114
	ds_bpermute_b32 v173, v245, v115
	ds_bpermute_b32 v174, v245, v106
	ds_bpermute_b32 v175, v245, v107
	s_waitcnt lgkmcnt(0)
	v_cndmask_b32_e64 v168, v168, v170, s[98:99]
	v_cndmask_b32_e64 v169, v169, v171, s[98:99]
	v_add_u32_e32 v170, 0x8000, v246
	global_store_dwordx2 v170, v[168:169], s[48:49]
	v_cndmask_b32_e64 v172, v172, v174, s[98:99]
	v_cndmask_b32_e64 v173, v173, v175, s[98:99]
	v_add_u32_e32 v174, 0xc000, v246
	global_store_dwordx2 v174, v[172:173], s[48:49]
	ds_bpermute_b32 v168, v244, v102
	ds_bpermute_b32 v169, v244, v103
	ds_bpermute_b32 v170, v244, v94
	ds_bpermute_b32 v171, v244, v95
	ds_bpermute_b32 v172, v245, v102
	ds_bpermute_b32 v173, v245, v103
	ds_bpermute_b32 v174, v245, v94
	ds_bpermute_b32 v175, v245, v95
	s_waitcnt lgkmcnt(0)
	v_cndmask_b32_e64 v168, v168, v170, s[98:99]
	v_cndmask_b32_e64 v169, v169, v171, s[98:99]
	v_add_u32_e32 v170, 0x8000, v246
	global_store_dwordx2 v170, v[168:169], s[48:49] offset:256
	v_cndmask_b32_e64 v172, v172, v174, s[98:99]
	v_cndmask_b32_e64 v173, v173, v175, s[98:99]
	v_add_u32_e32 v174, 0xc000, v246
	global_store_dwordx2 v174, v[172:173], s[48:49] offset:256
	global_load_dwordx4 v[168:171], v230, s[60:61]
	global_load_dwordx4 v[172:175], v230, s[60:61] offset:64
	global_load_dwordx4 v[176:179], v230, s[60:61] offset:512
	global_load_dwordx4 v[180:183], v230, s[60:61] offset:576
	s_waitcnt vmcnt(20)
	v_pk_add_f32 v[100:101], v[100:101], v[186:187]
	v_pk_add_f32 v[98:99], v[98:99], v[184:185]
	v_pk_add_f32 v[92:93], v[92:93], v[190:191]
	v_pk_add_f32 v[90:91], v[90:91], v[188:189]
	v_pk_add_f32 v[88:89], v[88:89], v[194:195]
	v_pk_add_f32 v[86:87], v[86:87], v[192:193]
	v_pk_add_f32 v[80:81], v[80:81], v[200:201]
	v_pk_add_f32 v[78:79], v[78:79], v[198:199]
	v_cvt_pk_bf16_f32 v98, v98, v99
	v_cvt_pk_bf16_f32 v99, v100, v101
	v_cvt_pk_bf16_f32 v90, v90, v91
	v_cvt_pk_bf16_f32 v91, v92, v93
	v_cvt_pk_bf16_f32 v86, v86, v87
	v_cvt_pk_bf16_f32 v87, v88, v89
	v_cvt_pk_bf16_f32 v78, v78, v79
	v_cvt_pk_bf16_f32 v79, v80, v81
	ds_bpermute_b32 v184, v244, v98
	ds_bpermute_b32 v185, v244, v99
	ds_bpermute_b32 v186, v244, v90
	ds_bpermute_b32 v187, v244, v91
	ds_bpermute_b32 v188, v245, v98
	ds_bpermute_b32 v189, v245, v99
	ds_bpermute_b32 v190, v245, v90
	ds_bpermute_b32 v191, v245, v91
	s_waitcnt lgkmcnt(0)
; DI unsigned pk_bf16(float a, float b) { f32x2 v = {a, b}; bf2_t r = __builtin_convertvector(v, bf2_t); return __builtin_bit_cast(unsigned, r); }
; DI float bflo(unsigned u) { return __uint_as_float(u << 16); }
; DI float bfhi(unsigned u) { return __uint_as_float(u & 0xffff0000u); }
;     DI void operator()(const f32x4 (&acc)[2][2][4][2], const Unit& u, int wr, int wc, int fr, int fq) const {
;     ...
;             for (int m = 0; m < 4; ++m) { const size_t o = (size_t)(row0 + ai * HALF + m * 16) * 1024 + col0;
; #pragma unroll
;                 for (int bj = 0; bj < 2; ++bj)
; #pragma unroll
;                     for (int n = 0; n < 2; ++n) { const size_t oo = o + bj * HALF + n * 16; f32x4 rv;
;                         if (RES_BF16) { const u32x2 t = *(const u32x2*)((const bf16_t*)res + oo); rv = (f32x4){bflo(t.x), bfhi(t.x), bflo(t.y), bfhi(t.y)}; }
;                         else rv = *(const f32x4*)((const float*)res + oo);
;                         const f32x4 v = acc[ai][bj][m][n] + rv; u32x2 w; w.x = pk_bf16(v.x, v.y); w.y = pk_bf16(v.z, v.w);
;                         *(u32x2*)(O + oo) = w; } }
	v_cndmask_b32_e64 v184, v184, v186, s[98:99]
	v_cndmask_b32_e64 v185, v185, v187, s[98:99]
	v_add_u32_e32 v186, 0x10000, v246
	global_store_dwordx2 v186, v[184:185], s[48:49]
	v_cndmask_b32_e64 v188, v188, v190, s[98:99]
	v_cndmask_b32_e64 v189, v189, v191, s[98:99]
	v_add_u32_e32 v190, 0x14000, v246
	global_store_dwordx2 v190, v[188:189], s[48:49]
	ds_bpermute_b32 v184, v244, v86
	ds_bpermute_b32 v185, v244, v87
	ds_bpermute_b32 v186, v244, v78
	ds_bpermute_b32 v187, v244, v79
	ds_bpermute_b32 v188, v245, v86
	ds_bpermute_b32 v189, v245, v87
	ds_bpermute_b32 v190, v245, v78
	ds_bpermute_b32 v191, v245, v79
	s_waitcnt lgkmcnt(0)
	v_cndmask_b32_e64 v184, v184, v186, s[98:99]
	v_cndmask_b32_e64 v185, v185, v187, s[98:99]
	v_add_u32_e32 v186, 0x10000, v246
	global_store_dwordx2 v186, v[184:185], s[48:49] offset:256
	v_cndmask_b32_e64 v188, v188, v190, s[98:99]
	v_cndmask_b32_e64 v189, v189, v191, s[98:99]
	v_add_u32_e32 v190, 0x14000, v246
	global_store_dwordx2 v190, v[188:189], s[48:49] offset:256
	global_load_dwordx4 v[184:187], v231, s[60:61]
	global_load_dwordx4 v[188:191], v231, s[60:61] offset:64
	global_load_dwordx4 v[192:195], v231, s[60:61] offset:512
	global_load_dwordx4 v[198:201], v231, s[60:61] offset:576
	s_waitcnt vmcnt(24)
	v_pk_add_f32 v[84:85], v[84:85], v[204:205]
	v_pk_add_f32 v[82:83], v[82:83], v[202:203]
	v_pk_add_f32 v[76:77], v[76:77], v[208:209]
	v_pk_add_f32 v[74:75], v[74:75], v[206:207]
	v_pk_add_f32 v[72:73], v[72:73], v[212:213]
	v_pk_add_f32 v[70:71], v[70:71], v[210:211]
	v_pk_add_f32 v[68:69], v[68:69], v[216:217]
	v_pk_add_f32 v[66:67], v[66:67], v[214:215]
	v_cvt_pk_bf16_f32 v82, v82, v83
	v_cvt_pk_bf16_f32 v83, v84, v85
	v_cvt_pk_bf16_f32 v74, v74, v75
	v_cvt_pk_bf16_f32 v75, v76, v77
	v_cvt_pk_bf16_f32 v70, v70, v71
	v_cvt_pk_bf16_f32 v71, v72, v73
	v_cvt_pk_bf16_f32 v66, v66, v67
	v_cvt_pk_bf16_f32 v67, v68, v69
	ds_bpermute_b32 v202, v244, v82
	ds_bpermute_b32 v203, v244, v83
	ds_bpermute_b32 v204, v244, v74
	ds_bpermute_b32 v205, v244, v75
	ds_bpermute_b32 v206, v245, v82
	ds_bpermute_b32 v207, v245, v83
	ds_bpermute_b32 v208, v245, v74
	ds_bpermute_b32 v209, v245, v75
	s_waitcnt lgkmcnt(0)
	v_cndmask_b32_e64 v202, v202, v204, s[98:99]
	v_cndmask_b32_e64 v203, v203, v205, s[98:99]
	v_add_u32_e32 v204, 0x18000, v246
	global_store_dwordx2 v204, v[202:203], s[48:49]
	v_cndmask_b32_e64 v206, v206, v208, s[98:99]
	v_cndmask_b32_e64 v207, v207, v209, s[98:99]
	v_add_u32_e32 v208, 0x1c000, v246
	global_store_dwordx2 v208, v[206:207], s[48:49]
	ds_bpermute_b32 v202, v244, v70
	ds_bpermute_b32 v203, v244, v71
	ds_bpermute_b32 v204, v244, v66
	ds_bpermute_b32 v205, v244, v67
	ds_bpermute_b32 v206, v245, v70
	ds_bpermute_b32 v207, v245, v71
	ds_bpermute_b32 v208, v245, v66
	ds_bpermute_b32 v209, v245, v67
	s_waitcnt lgkmcnt(0)
	v_cndmask_b32_e64 v202, v202, v204, s[98:99]
	v_cndmask_b32_e64 v203, v203, v205, s[98:99]
	v_add_u32_e32 v204, 0x18000, v246
	global_store_dwordx2 v204, v[202:203], s[48:49] offset:256
	v_cndmask_b32_e64 v206, v206, v208, s[98:99]
	v_cndmask_b32_e64 v207, v207, v209, s[98:99]
	v_add_u32_e32 v208, 0x1c000, v246
	global_store_dwordx2 v208, v[206:207], s[48:49] offset:256
	global_load_dwordx4 v[202:205], v232, s[60:61]
	global_load_dwordx4 v[206:209], v232, s[60:61] offset:64
	global_load_dwordx4 v[210:213], v232, s[60:61] offset:512
	global_load_dwordx4 v[214:217], v232, s[60:61] offset:576
	s_waitcnt vmcnt(24)
	v_pk_add_f32 v[64:65], v[64:65], v[142:143]
	v_pk_add_f32 v[62:63], v[62:63], v[140:141]
	v_pk_add_f32 v[60:61], v[60:61], v[156:157]
	v_pk_add_f32 v[58:59], v[58:59], v[154:155]
	v_pk_add_f32 v[56:57], v[56:57], v[160:161]
	v_pk_add_f32 v[54:55], v[54:55], v[158:159]
	v_pk_add_f32 v[48:49], v[48:49], v[166:167]
	v_pk_add_f32 v[46:47], v[46:47], v[164:165]
	v_cvt_pk_bf16_f32 v62, v62, v63
	v_cvt_pk_bf16_f32 v63, v64, v65
	v_cvt_pk_bf16_f32 v58, v58, v59
	v_cvt_pk_bf16_f32 v59, v60, v61
	v_cvt_pk_bf16_f32 v54, v54, v55
	v_cvt_pk_bf16_f32 v55, v56, v57
	v_cvt_pk_bf16_f32 v46, v46, v47
	v_cvt_pk_bf16_f32 v47, v48, v49
	ds_bpermute_b32 v140, v244, v62
	ds_bpermute_b32 v141, v244, v63
	ds_bpermute_b32 v142, v244, v58
	ds_bpermute_b32 v143, v244, v59
	ds_bpermute_b32 v154, v245, v62
	ds_bpermute_b32 v155, v245, v63
	ds_bpermute_b32 v156, v245, v58
	ds_bpermute_b32 v157, v245, v59
	s_waitcnt lgkmcnt(0)
	v_cndmask_b32_e64 v140, v140, v142, s[98:99]
	v_cndmask_b32_e64 v141, v141, v143, s[98:99]
	v_add_u32_e32 v142, 0x40000, v246
	global_store_dwordx2 v142, v[140:141], s[48:49]
	v_cndmask_b32_e64 v154, v154, v156, s[98:99]
	v_cndmask_b32_e64 v155, v155, v157, s[98:99]
	v_add_u32_e32 v156, 0x44000, v246
	global_store_dwordx2 v156, v[154:155], s[48:49]
	ds_bpermute_b32 v140, v244, v54
	ds_bpermute_b32 v141, v244, v55
	ds_bpermute_b32 v142, v244, v46
	ds_bpermute_b32 v143, v244, v47
	ds_bpermute_b32 v154, v245, v54
	ds_bpermute_b32 v155, v245, v55
	ds_bpermute_b32 v156, v245, v46
	ds_bpermute_b32 v157, v245, v47
	s_waitcnt lgkmcnt(0)
	v_cndmask_b32_e64 v140, v140, v142, s[98:99]
	v_cndmask_b32_e64 v141, v141, v143, s[98:99]
	v_add_u32_e32 v142, 0x40000, v246
	global_store_dwordx2 v142, v[140:141], s[48:49] offset:256
	v_cndmask_b32_e64 v154, v154, v156, s[98:99]
	v_cndmask_b32_e64 v155, v155, v157, s[98:99]
	v_add_u32_e32 v156, 0x44000, v246
	global_store_dwordx2 v156, v[154:155], s[48:49] offset:256
	s_waitcnt vmcnt(20)
; DI unsigned pk_bf16(float a, float b) { f32x2 v = {a, b}; bf2_t r = __builtin_convertvector(v, bf2_t); return __builtin_bit_cast(unsigned, r); }
; DI float bflo(unsigned u) { return __uint_as_float(u << 16); }
; DI float bfhi(unsigned u) { return __uint_as_float(u & 0xffff0000u); }
;     DI void operator()(const f32x4 (&acc)[2][2][4][2], const Unit& u, int wr, int wc, int fr, int fq) const {
;     ...
;             for (int m = 0; m < 4; ++m) { const size_t o = (size_t)(row0 + ai * HALF + m * 16) * 1024 + col0;
; #pragma unroll
;                 for (int bj = 0; bj < 2; ++bj)
; #pragma unroll
;                     for (int n = 0; n < 2; ++n) { const size_t oo = o + bj * HALF + n * 16; f32x4 rv;
;                         if (RES_BF16) { const u32x2 t = *(const u32x2*)((const bf16_t*)res + oo); rv = (f32x4){bflo(t.x), bfhi(t.x), bflo(t.y), bfhi(t.y)}; }
;                         else rv = *(const f32x4*)((const float*)res + oo);
;                         const f32x4 v = acc[ai][bj][m][n] + rv; u32x2 w; w.x = pk_bf16(v.x, v.y); w.y = pk_bf16(v.z, v.w);
;                         *(u32x2*)(O + oo) = w; } }
; template <class Epi, class Sched>
; DI void gemm_phase(LAS unsigned char* lds, const Gemm g, const Sched& S, const Epi& E) {
;     ...
;         if (!has_next) break;
	v_pk_add_f32 v[52:53], v[52:53], v[170:171]
	v_pk_add_f32 v[50:51], v[50:51], v[168:169]
	v_pk_add_f32 v[44:45], v[44:45], v[174:175]
	v_pk_add_f32 v[42:43], v[42:43], v[172:173]
	v_pk_add_f32 v[40:41], v[40:41], v[178:179]
	v_pk_add_f32 v[38:39], v[38:39], v[176:177]
	v_pk_add_f32 v[32:33], v[32:33], v[182:183]
	v_pk_add_f32 v[30:31], v[30:31], v[180:181]
	v_cvt_pk_bf16_f32 v50, v50, v51
	v_cvt_pk_bf16_f32 v51, v52, v53
	v_cvt_pk_bf16_f32 v42, v42, v43
	v_cvt_pk_bf16_f32 v43, v44, v45
	v_cvt_pk_bf16_f32 v38, v38, v39
	v_cvt_pk_bf16_f32 v39, v40, v41
	v_cvt_pk_bf16_f32 v30, v30, v31
	v_cvt_pk_bf16_f32 v31, v32, v33
	ds_bpermute_b32 v168, v244, v50
	ds_bpermute_b32 v169, v244, v51
	ds_bpermute_b32 v170, v244, v42
	ds_bpermute_b32 v171, v244, v43
	ds_bpermute_b32 v172, v245, v50
	ds_bpermute_b32 v173, v245, v51
	ds_bpermute_b32 v174, v245, v42
	ds_bpermute_b32 v175, v245, v43
	s_waitcnt lgkmcnt(0)
	v_cndmask_b32_e64 v168, v168, v170, s[98:99]
	v_cndmask_b32_e64 v169, v169, v171, s[98:99]
	v_add_u32_e32 v170, 0x48000, v246
	global_store_dwordx2 v170, v[168:169], s[48:49]
	v_cndmask_b32_e64 v172, v172, v174, s[98:99]
	v_cndmask_b32_e64 v173, v173, v175, s[98:99]
	v_add_u32_e32 v174, 0x4c000, v246
	global_store_dwordx2 v174, v[172:173], s[48:49]
	ds_bpermute_b32 v168, v244, v38
	ds_bpermute_b32 v169, v244, v39
	ds_bpermute_b32 v170, v244, v30
	ds_bpermute_b32 v171, v244, v31
	ds_bpermute_b32 v172, v245, v38
	ds_bpermute_b32 v173, v245, v39
	ds_bpermute_b32 v174, v245, v30
	ds_bpermute_b32 v175, v245, v31
	s_waitcnt lgkmcnt(0)
	v_cndmask_b32_e64 v168, v168, v170, s[98:99]
	v_cndmask_b32_e64 v169, v169, v171, s[98:99]
	v_add_u32_e32 v170, 0x48000, v246
	global_store_dwordx2 v170, v[168:169], s[48:49] offset:256
	v_cndmask_b32_e64 v172, v172, v174, s[98:99]
	v_cndmask_b32_e64 v173, v173, v175, s[98:99]
	v_add_u32_e32 v174, 0x4c000, v246
	global_store_dwordx2 v174, v[172:173], s[48:49] offset:256
	s_waitcnt vmcnt(16)
	v_pk_add_f32 v[36:37], v[36:37], v[186:187]
	v_pk_add_f32 v[34:35], v[34:35], v[184:185]
	v_pk_add_f32 v[28:29], v[28:29], v[190:191]
	v_pk_add_f32 v[26:27], v[26:27], v[188:189]
	v_pk_add_f32 v[24:25], v[24:25], v[194:195]
	v_pk_add_f32 v[22:23], v[22:23], v[192:193]
	v_pk_add_f32 v[16:17], v[16:17], v[200:201]
	v_pk_add_f32 v[14:15], v[14:15], v[198:199]
	v_cvt_pk_bf16_f32 v34, v34, v35
	v_cvt_pk_bf16_f32 v35, v36, v37
	v_cvt_pk_bf16_f32 v26, v26, v27
	v_cvt_pk_bf16_f32 v27, v28, v29
	v_cvt_pk_bf16_f32 v22, v22, v23
	v_cvt_pk_bf16_f32 v23, v24, v25
	v_cvt_pk_bf16_f32 v14, v14, v15
	v_cvt_pk_bf16_f32 v15, v16, v17
	ds_bpermute_b32 v184, v244, v34
	ds_bpermute_b32 v185, v244, v35
	ds_bpermute_b32 v186, v244, v26
	ds_bpermute_b32 v187, v244, v27
	ds_bpermute_b32 v188, v245, v34
	ds_bpermute_b32 v189, v245, v35
	ds_bpermute_b32 v190, v245, v26
	ds_bpermute_b32 v191, v245, v27
	s_waitcnt lgkmcnt(0)
	v_cndmask_b32_e64 v184, v184, v186, s[98:99]
	v_cndmask_b32_e64 v185, v185, v187, s[98:99]
	v_add_u32_e32 v186, 0x50000, v246
	global_store_dwordx2 v186, v[184:185], s[48:49]
	v_cndmask_b32_e64 v188, v188, v190, s[98:99]
	v_cndmask_b32_e64 v189, v189, v191, s[98:99]
	v_add_u32_e32 v190, 0x54000, v246
	global_store_dwordx2 v190, v[188:189], s[48:49]
	ds_bpermute_b32 v184, v244, v22
	ds_bpermute_b32 v185, v244, v23
	ds_bpermute_b32 v186, v244, v14
	ds_bpermute_b32 v187, v244, v15
	ds_bpermute_b32 v188, v245, v22
	ds_bpermute_b32 v189, v245, v23
	ds_bpermute_b32 v190, v245, v14
	ds_bpermute_b32 v191, v245, v15
	s_waitcnt lgkmcnt(0)
	v_cndmask_b32_e64 v184, v184, v186, s[98:99]
	v_cndmask_b32_e64 v185, v185, v187, s[98:99]
	v_add_u32_e32 v186, 0x50000, v246
	global_store_dwordx2 v186, v[184:185], s[48:49] offset:256
	v_cndmask_b32_e64 v188, v188, v190, s[98:99]
	v_cndmask_b32_e64 v189, v189, v191, s[98:99]
	v_add_u32_e32 v190, 0x54000, v246
	global_store_dwordx2 v190, v[188:189], s[48:49] offset:256
	s_waitcnt vmcnt(12)
	v_pk_add_f32 v[20:21], v[20:21], v[204:205]
	v_pk_add_f32 v[18:19], v[18:19], v[202:203]
	v_pk_add_f32 v[12:13], v[12:13], v[208:209]
	v_pk_add_f32 v[10:11], v[10:11], v[206:207]
	v_pk_add_f32 v[8:9], v[8:9], v[212:213]
	v_pk_add_f32 v[6:7], v[6:7], v[210:211]
	v_pk_add_f32 v[4:5], v[4:5], v[216:217]
	v_pk_add_f32 v[2:3], v[2:3], v[214:215]
	v_cvt_pk_bf16_f32 v18, v18, v19
	v_cvt_pk_bf16_f32 v19, v20, v21
	v_cvt_pk_bf16_f32 v10, v10, v11
	v_cvt_pk_bf16_f32 v11, v12, v13
	v_cvt_pk_bf16_f32 v6, v6, v7
	v_cvt_pk_bf16_f32 v7, v8, v9
	v_cvt_pk_bf16_f32 v2, v2, v3
	v_cvt_pk_bf16_f32 v3, v4, v5
	ds_bpermute_b32 v202, v244, v18
	ds_bpermute_b32 v203, v244, v19
	ds_bpermute_b32 v204, v244, v10
	ds_bpermute_b32 v205, v244, v11
	ds_bpermute_b32 v206, v245, v18
	ds_bpermute_b32 v207, v245, v19
	ds_bpermute_b32 v208, v245, v10
	ds_bpermute_b32 v209, v245, v11
	s_waitcnt lgkmcnt(0)
	v_cndmask_b32_e64 v202, v202, v204, s[98:99]
	v_cndmask_b32_e64 v203, v203, v205, s[98:99]
	v_add_u32_e32 v204, 0x58000, v246
	global_store_dwordx2 v204, v[202:203], s[48:49]
	v_cndmask_b32_e64 v206, v206, v208, s[98:99]
	v_cndmask_b32_e64 v207, v207, v209, s[98:99]
	v_add_u32_e32 v208, 0x5c000, v246
	global_store_dwordx2 v208, v[206:207], s[48:49]
	ds_bpermute_b32 v202, v244, v6
	ds_bpermute_b32 v203, v244, v7
	ds_bpermute_b32 v204, v244, v2
	ds_bpermute_b32 v205, v244, v3
	ds_bpermute_b32 v206, v245, v6
	ds_bpermute_b32 v207, v245, v7
	ds_bpermute_b32 v208, v245, v2
	ds_bpermute_b32 v209, v245, v3
	s_waitcnt lgkmcnt(0)
	v_cndmask_b32_e64 v202, v202, v204, s[98:99]
	v_cndmask_b32_e64 v203, v203, v205, s[98:99]
	v_add_u32_e32 v204, 0x58000, v246
	global_store_dwordx2 v204, v[202:203], s[48:49] offset:256
	v_cndmask_b32_e64 v206, v206, v208, s[98:99]
	v_cndmask_b32_e64 v207, v207, v209, s[98:99]
	v_add_u32_e32 v208, 0x5c000, v246
	global_store_dwordx2 v208, v[206:207], s[48:49] offset:256
	s_cbranch_vccz .LBB0_1006
	s_waitcnt vmcnt(0)
	s_cmpk_gt_u32 s3, 0xff
	s_cbranch_scc1 .LBB0_1011
	s_barrier

; #define PG8_STAGE(bufoff, gbase, voff) do { _Pragma("unroll") for (int _i = 0; _i < 2; ++_i) \
;         __builtin_amdgcn_global_load_lds((const unsigned*)((const char*)(gbase) + (voff)[_i]), (LAS unsigned*)(lds + (bufoff) + ldsw + _i * 8192), 16, 0, 0); } while (0)
; #define PG8_LDA(dst, b, h) do { _Pragma("unroll") for (int m = 0; m < 4; ++m) _Pragma("unroll") for (int k = 0; k < 2; ++k) dst[m][k] = *(const LAS bf16x8*)(lds + PG8_SA(b, h) + aoff + m * 2048 + k * 1024); } while (0)
; #define PG8_LDB(dst, b, h) do { _Pragma("unroll") for (int n = 0; n < 2; ++n) _Pragma("unroll") for (int k = 0; k < 2; ++k) dst[n][k] = *(const LAS bf16x8*)(lds + PG8_SB(b, h) + boff + n * 2048 + k * 1024); } while (0)
; #define PG8_MMA(ai, bj, At, Bt) do { __builtin_amdgcn_s_setprio(1); _Pragma("unroll") for (int m = 0; m < 4; ++m) _Pragma("unroll") for (int n = 0; n < 2; ++n) _Pragma("unroll") for (int k = 0; k < 2; ++k) \
;         acc[ai][bj][m][n] = __builtin_amdgcn_mfma_f32_16x16x32_bf16(Bt[n][k], At[m][k], acc[ai][bj][m][n], 0, 0, 0); __builtin_amdgcn_s_setprio(0); } while (0)
; #define PG8_WAIT_L(n) asm volatile("s_waitcnt lgkmcnt(" #n ")" ::: "memory")
; #define PG8_BAR __builtin_amdgcn_s_barrier()
; #define PG8_SCHED __builtin_amdgcn_sched_barrier(0)
; template <class Epi, class Sched>
; DI void gemm_phase(LAS unsigned char* lds, const Gemm g, const Sched& S, const Epi& E) {
;     ...
;             PG8_LDB(B0, 0, 0); PG8_SCHED; PG8_LDA(At, 0, 0); PG8_STAGE(PG8_SA(1, 1), a1 + hstep, voffA);
;             PG8_WAIT_L(8); PG8_BAR; PG8_WAIT_L(0); PG8_MMA(0, 0, At, B0); PG8_BAR; PG8_SCHED;
;             PG8_LDB(B1, 0, 1); PG8_STAGE(PG8_SB(0, 0), b2, voffB);
;             PG8_BAR; PG8_WAIT_L(0); PG8_MMA(0, 1, At, B1); PG8_BAR;
;             PG8_LDA(At, 0, 1); PG8_STAGE(PG8_SA(0, 0), a2, voffA);
;             PG8_BAR; PG8_WAIT_L(0); PG8_MMA(1, 0, At, B0); PG8_BAR; PG8_SCHED;
.LBB0_1523:
	ds_read_b128 v[140:143], v146
	ds_read_b128 v[150:153], v146 offset:1024
	ds_read_b128 v[154:157], v146 offset:2048
	ds_read_b128 v[158:161], v146 offset:3072
	s_add_u32 s50, s42, 0xfff80080
	s_addc_u32 s51, s43, -1
	s_cmp_eq_u32 s73, 28
	s_cselect_b32 s53, s67, s51
	s_cselect_b32 s52, s68, s50
	s_cselect_b32 s51, s69, s72
	s_cselect_b32 s50, s70, s71
	v_lshl_add_u64 v[202:203], s[42:43], 0, v[136:137]
	s_add_i32 m0, s47, 0xc000
	ds_read_b128 v[168:171], v147
	ds_read_b128 v[172:175], v147 offset:1024
	ds_read_b128 v[176:179], v147 offset:2048
	ds_read_b128 v[180:183], v147 offset:3072
	ds_read_b128 v[184:187], v147 offset:4096
	ds_read_b128 v[188:191], v147 offset:5120
	ds_read_b128 v[192:195], v147 offset:6144
	ds_read_b128 v[198:201], v147 offset:7168
	global_load_lds_dwordx4 v[202:203], off
	v_lshl_add_u64 v[202:203], s[42:43], 0, v[138:139]
	s_add_i32 m0, s47, 0xe000
	s_nop 0
	global_load_lds_dwordx4 v[202:203], off
	s_waitcnt lgkmcnt(8)
	s_barrier
	s_waitcnt lgkmcnt(0)
	s_setprio 1
	s_waitcnt lgkmcnt(0)
	v_mfma_f32_16x16x32_bf16 v[126:129], v[140:143], v[168:171], v[126:129]
	v_mfma_f32_16x16x32_bf16 v[122:125], v[154:157], v[168:171], v[122:125]
	v_mfma_f32_16x16x32_bf16 v[110:113], v[140:143], v[176:179], v[110:113]
	v_mfma_f32_16x16x32_bf16 v[106:109], v[154:157], v[176:179], v[106:109]
	v_mfma_f32_16x16x32_bf16 v[94:97], v[140:143], v[184:187], v[94:97]
	v_mfma_f32_16x16x32_bf16 v[90:93], v[154:157], v[184:187], v[90:93]
	v_mfma_f32_16x16x32_bf16 v[78:81], v[140:143], v[192:195], v[78:81]
	v_mfma_f32_16x16x32_bf16 v[74:77], v[154:157], v[192:195], v[74:77]
	v_mfma_f32_16x16x32_bf16 v[126:129], v[150:153], v[172:175], v[126:129]
	v_mfma_f32_16x16x32_bf16 v[122:125], v[158:161], v[172:175], v[122:125]
	v_mfma_f32_16x16x32_bf16 v[110:113], v[150:153], v[180:183], v[110:113]
	v_mfma_f32_16x16x32_bf16 v[106:109], v[158:161], v[180:183], v[106:109]
	v_mfma_f32_16x16x32_bf16 v[94:97], v[150:153], v[188:191], v[94:97]
	v_mfma_f32_16x16x32_bf16 v[90:93], v[158:161], v[188:191], v[90:93]
	v_mfma_f32_16x16x32_bf16 v[78:81], v[150:153], v[198:201], v[78:81]
	v_mfma_f32_16x16x32_bf16 v[74:77], v[158:161], v[198:201], v[74:77]
	s_setprio 0
	s_barrier
	s_add_i32 s83, s63, s33
	v_lshl_add_u64 v[218:219], s[50:51], 0, v[132:133]
	s_mov_b32 m0, s83
	ds_read_b128 v[202:205], v148
	ds_read_b128 v[206:209], v148 offset:1024
	ds_read_b128 v[210:213], v148 offset:2048
	ds_read_b128 v[214:217], v148 offset:3072
	global_load_lds_dwordx4 v[218:219], off
	v_lshl_add_u64 v[220:221], s[50:51], 0, v[130:131]
	s_add_i32 m0, s83, 0x2000
	s_nop 0
	global_load_lds_dwordx4 v[220:221], off
	s_barrier
	s_waitcnt lgkmcnt(0)
	s_setprio 1
	s_waitcnt lgkmcnt(0)
	v_mfma_f32_16x16x32_bf16 v[118:121], v[202:205], v[168:171], v[118:121]
	v_mfma_f32_16x16x32_bf16 v[114:117], v[210:213], v[168:171], v[114:117]
	v_mfma_f32_16x16x32_bf16 v[102:105], v[202:205], v[176:179], v[102:105]
	v_mfma_f32_16x16x32_bf16 v[98:101], v[210:213], v[176:179], v[98:101]
	v_mfma_f32_16x16x32_bf16 v[86:89], v[202:205], v[184:187], v[86:89]
	v_mfma_f32_16x16x32_bf16 v[82:85], v[210:213], v[184:187], v[82:85]
	v_mfma_f32_16x16x32_bf16 v[70:73], v[202:205], v[192:195], v[70:73]
	v_mfma_f32_16x16x32_bf16 v[66:69], v[210:213], v[192:195], v[66:69]
	v_mfma_f32_16x16x32_bf16 v[118:121], v[206:209], v[172:175], v[118:121]
	v_mfma_f32_16x16x32_bf16 v[114:117], v[214:217], v[172:175], v[114:117]
	v_mfma_f32_16x16x32_bf16 v[102:105], v[206:209], v[180:183], v[102:105]
	v_mfma_f32_16x16x32_bf16 v[98:101], v[214:217], v[180:183], v[98:101]
	v_mfma_f32_16x16x32_bf16 v[86:89], v[206:209], v[188:191], v[86:89]
	v_mfma_f32_16x16x32_bf16 v[82:85], v[214:217], v[188:191], v[82:85]
	v_mfma_f32_16x16x32_bf16 v[70:73], v[206:209], v[198:201], v[70:73]
	v_mfma_f32_16x16x32_bf16 v[66:69], v[214:217], v[198:201], v[66:69]
	s_setprio 0
	s_mov_b32 m0, s47
	v_lshl_add_u64 v[222:223], s[52:53], 0, v[132:133]
	s_barrier
	ds_read_b128 v[168:171], v147 offset:16384
	ds_read_b128 v[172:175], v147 offset:17408
	ds_read_b128 v[176:179], v147 offset:18432
	ds_read_b128 v[180:183], v147 offset:19456
	ds_read_b128 v[184:187], v147 offset:20480
	ds_read_b128 v[188:191], v147 offset:21504
	ds_read_b128 v[192:195], v147 offset:22528
	ds_read_b128 v[198:201], v147 offset:23552
	global_load_lds_dwordx4 v[222:223], off
	v_lshl_add_u64 v[224:225], s[52:53], 0, v[130:131]
	s_mov_b32 m0, s54
	s_nop 0
	global_load_lds_dwordx4 v[224:225], off
	s_barrier
	s_waitcnt lgkmcnt(0)
	s_setprio 1
	s_waitcnt lgkmcnt(0)
	v_mfma_f32_16x16x32_bf16 v[62:65], v[140:143], v[168:171], v[62:65]
	v_mfma_f32_16x16x32_bf16 v[58:61], v[154:157], v[168:171], v[58:61]
	v_mfma_f32_16x16x32_bf16 v[46:49], v[140:143], v[176:179], v[46:49]
	v_mfma_f32_16x16x32_bf16 v[42:45], v[154:157], v[176:179], v[42:45]
	v_mfma_f32_16x16x32_bf16 v[30:33], v[140:143], v[184:187], v[30:33]
	v_mfma_f32_16x16x32_bf16 v[26:29], v[154:157], v[184:187], v[26:29]
	v_mfma_f32_16x16x32_bf16 v[14:17], v[140:143], v[192:195], v[14:17]
	v_mfma_f32_16x16x32_bf16 v[10:13], v[154:157], v[192:195], v[10:13]
	v_mfma_f32_16x16x32_bf16 v[62:65], v[150:153], v[172:175], v[62:65]
	v_mfma_f32_16x16x32_bf16 v[58:61], v[158:161], v[172:175], v[58:61]
	v_mfma_f32_16x16x32_bf16 v[46:49], v[150:153], v[180:183], v[46:49]
	v_mfma_f32_16x16x32_bf16 v[42:45], v[158:161], v[180:183], v[42:45]
	v_mfma_f32_16x16x32_bf16 v[30:33], v[150:153], v[188:191], v[30:33]
	v_mfma_f32_16x16x32_bf16 v[26:29], v[158:161], v[188:191], v[26:29]
	v_mfma_f32_16x16x32_bf16 v[14:17], v[150:153], v[198:201], v[14:17]
	v_mfma_f32_16x16x32_bf16 v[10:13], v[158:161], v[198:201], v[10:13]
	s_setprio 0
	s_barrier
; #define PG8_STAGE(bufoff, gbase, voff) do { _Pragma("unroll") for (int _i = 0; _i < 2; ++_i) \
;         __builtin_amdgcn_global_load_lds((const unsigned*)((const char*)(gbase) + (voff)[_i]), (LAS unsigned*)(lds + (bufoff) + ldsw + _i * 8192), 16, 0, 0); } while (0)
; #define PG8_LDA(dst, b, h) do { _Pragma("unroll") for (int m = 0; m < 4; ++m) _Pragma("unroll") for (int k = 0; k < 2; ++k) dst[m][k] = *(const LAS bf16x8*)(lds + PG8_SA(b, h) + aoff + m * 2048 + k * 1024); } while (0)
; #define PG8_LDB(dst, b, h) do { _Pragma("unroll") for (int n = 0; n < 2; ++n) _Pragma("unroll") for (int k = 0; k < 2; ++k) dst[n][k] = *(const LAS bf16x8*)(lds + PG8_SB(b, h) + boff + n * 2048 + k * 1024); } while (0)
; #define PG8_MMA(ai, bj, At, Bt) do { __builtin_amdgcn_s_setprio(1); _Pragma("unroll") for (int m = 0; m < 4; ++m) _Pragma("unroll") for (int n = 0; n < 2; ++n) _Pragma("unroll") for (int k = 0; k < 2; ++k) \
;         acc[ai][bj][m][n] = __builtin_amdgcn_mfma_f32_16x16x32_bf16(Bt[n][k], At[m][k], acc[ai][bj][m][n], 0, 0, 0); __builtin_amdgcn_s_setprio(0); } while (0)
; #define PG8_WAIT_V(n) asm volatile("s_waitcnt vmcnt(" #n ")" ::: "memory")
; #define PG8_WAIT_L(n) asm volatile("s_waitcnt lgkmcnt(" #n ")" ::: "memory")
; #define PG8_BAR __builtin_amdgcn_s_barrier()
; #define PG8_SCHED __builtin_amdgcn_sched_barrier(0)
; template <class Epi, class Sched>
; DI void gemm_phase(LAS unsigned char* lds, const Gemm g, const Sched& S, const Epi& E) {
;     ...
;             PG8_STAGE(PG8_SB(0, 1), b2 + hstep, voffB);
;             PG8_WAIT_V(6); PG8_BAR; PG8_MMA(1, 1, At, B1); PG8_BAR;
;             PG8_LDB(B0, 1, 0); PG8_SCHED; PG8_LDA(At, 1, 0); PG8_STAGE(PG8_SA(0, 1), a2 + hstep, voffA);
;             PG8_WAIT_L(8); PG8_BAR; PG8_WAIT_L(0); PG8_MMA(0, 0, At, B0); PG8_BAR; PG8_SCHED;
;             PG8_LDB(B1, 1, 1); PG8_STAGE(PG8_SB(1, 0), b3, voffB);
;             PG8_BAR; PG8_WAIT_L(0); PG8_MMA(0, 1, At, B1); PG8_BAR;
;             PG8_LDA(At, 1, 1); PG8_STAGE(PG8_SA(1, 0), a3, voffA);
;             PG8_BAR; PG8_WAIT_L(0); PG8_MMA(1, 0, At, B0); PG8_BAR; PG8_SCHED;
	s_add_u32 s88, s50, 0x80000
	s_addc_u32 s89, s51, 0
	s_add_i32 s83, s64, s33
	v_lshl_add_u64 v[140:141], s[88:89], 0, v[132:133]
	s_mov_b32 m0, s83
	s_nop 0
	global_load_lds_dwordx4 v[140:141], off
	v_lshl_add_u64 v[140:141], s[88:89], 0, v[130:131]
	s_add_i32 m0, s83, 0x2000
	s_nop 0
	global_load_lds_dwordx4 v[140:141], off
	s_waitcnt vmcnt(6)
	s_barrier
	s_setprio 1
	v_mfma_f32_16x16x32_bf16 v[54:57], v[202:205], v[168:171], v[54:57]
	v_mfma_f32_16x16x32_bf16 v[50:53], v[210:213], v[168:171], v[50:53]
	v_mfma_f32_16x16x32_bf16 v[38:41], v[202:205], v[176:179], v[38:41]
	v_mfma_f32_16x16x32_bf16 v[34:37], v[210:213], v[176:179], v[34:37]
	v_mfma_f32_16x16x32_bf16 v[22:25], v[202:205], v[184:187], v[22:25]
	v_mfma_f32_16x16x32_bf16 v[18:21], v[210:213], v[184:187], v[18:21]
	v_mfma_f32_16x16x32_bf16 v[6:9], v[202:205], v[192:195], v[6:9]
	v_mfma_f32_16x16x32_bf16 v[2:5], v[210:213], v[192:195], v[2:5]
	v_mfma_f32_16x16x32_bf16 v[54:57], v[206:209], v[172:175], v[54:57]
	v_mfma_f32_16x16x32_bf16 v[50:53], v[214:217], v[172:175], v[50:53]
	v_mfma_f32_16x16x32_bf16 v[38:41], v[206:209], v[180:183], v[38:41]
	v_mfma_f32_16x16x32_bf16 v[34:37], v[214:217], v[180:183], v[34:37]
	v_mfma_f32_16x16x32_bf16 v[22:25], v[206:209], v[188:191], v[22:25]
	v_mfma_f32_16x16x32_bf16 v[18:21], v[214:217], v[188:191], v[18:21]
	v_mfma_f32_16x16x32_bf16 v[6:9], v[206:209], v[198:201], v[6:9]
	v_mfma_f32_16x16x32_bf16 v[2:5], v[214:217], v[198:201], v[2:5]
	s_setprio 0
	s_add_i32 s83, 0, 0x18000
	v_add_u32_e32 v134, s83, v145
	s_barrier
	ds_read_b128 v[140:143], v134
	ds_read_b128 v[150:153], v134 offset:1024
	ds_read_b128 v[154:157], v134 offset:2048
	ds_read_b128 v[158:161], v134 offset:3072
	s_add_u32 s52, s52, 0x80000
	s_addc_u32 s53, s53, 0
	s_mov_b32 m0, s55
	v_lshl_add_u64 v[202:203], s[52:53], 0, v[132:133]
	ds_read_b128 v[168:171], v147 offset:32768
	ds_read_b128 v[172:175], v147 offset:33792
	ds_read_b128 v[176:179], v147 offset:34816
	ds_read_b128 v[180:183], v147 offset:35840
	ds_read_b128 v[184:187], v147 offset:36864
	ds_read_b128 v[188:191], v147 offset:37888
	ds_read_b128 v[192:195], v147 offset:38912
	ds_read_b128 v[198:201], v147 offset:39936
	global_load_lds_dwordx4 v[202:203], off
	v_lshl_add_u64 v[202:203], s[52:53], 0, v[130:131]
	s_mov_b32 m0, s57
	s_nop 0
	global_load_lds_dwordx4 v[202:203], off
	s_waitcnt lgkmcnt(8)
	s_barrier
	s_waitcnt lgkmcnt(0)
	s_setprio 1
	s_waitcnt lgkmcnt(0)
	v_mfma_f32_16x16x32_bf16 v[126:129], v[140:143], v[168:171], v[126:129]
	v_mfma_f32_16x16x32_bf16 v[122:125], v[154:157], v[168:171], v[122:125]
	v_mfma_f32_16x16x32_bf16 v[110:113], v[140:143], v[176:179], v[110:113]
	v_mfma_f32_16x16x32_bf16 v[106:109], v[154:157], v[176:179], v[106:109]
	v_mfma_f32_16x16x32_bf16 v[94:97], v[140:143], v[184:187], v[94:97]
	v_mfma_f32_16x16x32_bf16 v[90:93], v[154:157], v[184:187], v[90:93]
	v_mfma_f32_16x16x32_bf16 v[78:81], v[140:143], v[192:195], v[78:81]
	v_mfma_f32_16x16x32_bf16 v[74:77], v[154:157], v[192:195], v[74:77]
	v_mfma_f32_16x16x32_bf16 v[126:129], v[150:153], v[172:175], v[126:129]
	v_mfma_f32_16x16x32_bf16 v[122:125], v[158:161], v[172:175], v[122:125]
	v_mfma_f32_16x16x32_bf16 v[110:113], v[150:153], v[180:183], v[110:113]
	v_mfma_f32_16x16x32_bf16 v[106:109], v[158:161], v[180:183], v[106:109]
	v_mfma_f32_16x16x32_bf16 v[94:97], v[150:153], v[188:191], v[94:97]
	v_mfma_f32_16x16x32_bf16 v[90:93], v[158:161], v[188:191], v[90:93]
	v_mfma_f32_16x16x32_bf16 v[78:81], v[150:153], v[198:201], v[78:81]
	v_mfma_f32_16x16x32_bf16 v[74:77], v[158:161], v[198:201], v[74:77]
	s_setprio 0
	s_barrier
	s_add_i32 s52, 0, 0x1c000
	s_add_i32 s53, s83, s33
	v_add_u32_e32 v134, s52, v145
	v_lshl_add_u64 v[218:219], v[218:219], 0, s[10:11]
	s_mov_b32 m0, s53
	ds_read_b128 v[202:205], v134
	ds_read_b128 v[206:209], v134 offset:1024
	ds_read_b128 v[210:213], v134 offset:2048
	ds_read_b128 v[214:217], v134 offset:3072
	global_load_lds_dwordx4 v[218:219], off
	v_lshl_add_u64 v[218:219], v[220:221], 0, s[10:11]
	s_add_i32 m0, s53, 0x2000
	s_nop 0
	global_load_lds_dwordx4 v[218:219], off
	s_barrier
	s_waitcnt lgkmcnt(0)
	s_setprio 1
	s_waitcnt lgkmcnt(0)
	v_mfma_f32_16x16x32_bf16 v[118:121], v[202:205], v[168:171], v[118:121]
	v_mfma_f32_16x16x32_bf16 v[114:117], v[210:213], v[168:171], v[114:117]
	v_mfma_f32_16x16x32_bf16 v[102:105], v[202:205], v[176:179], v[102:105]
	v_mfma_f32_16x16x32_bf16 v[98:101], v[210:213], v[176:179], v[98:101]
	v_mfma_f32_16x16x32_bf16 v[86:89], v[202:205], v[184:187], v[86:89]
	v_mfma_f32_16x16x32_bf16 v[82:85], v[210:213], v[184:187], v[82:85]
	v_mfma_f32_16x16x32_bf16 v[70:73], v[202:205], v[192:195], v[70:73]
	v_mfma_f32_16x16x32_bf16 v[66:69], v[210:213], v[192:195], v[66:69]
	v_mfma_f32_16x16x32_bf16 v[118:121], v[206:209], v[172:175], v[118:121]
	v_mfma_f32_16x16x32_bf16 v[114:117], v[214:217], v[172:175], v[114:117]
	v_mfma_f32_16x16x32_bf16 v[102:105], v[206:209], v[180:183], v[102:105]
	v_mfma_f32_16x16x32_bf16 v[98:101], v[214:217], v[180:183], v[98:101]
	v_mfma_f32_16x16x32_bf16 v[86:89], v[206:209], v[188:191], v[86:89]
	v_mfma_f32_16x16x32_bf16 v[82:85], v[214:217], v[188:191], v[82:85]
	v_mfma_f32_16x16x32_bf16 v[70:73], v[206:209], v[198:201], v[70:73]
	v_mfma_f32_16x16x32_bf16 v[66:69], v[214:217], v[198:201], v[66:69]
	s_setprio 0
	s_mov_b32 m0, s59
	v_lshl_add_u64 v[218:219], v[222:223], 0, s[10:11]
	s_barrier
	ds_read_b128 v[168:171], v147 offset:49152
	ds_read_b128 v[172:175], v147 offset:50176
	ds_read_b128 v[176:179], v147 offset:51200
	ds_read_b128 v[180:183], v147 offset:52224
	ds_read_b128 v[184:187], v147 offset:53248
	ds_read_b128 v[188:191], v147 offset:54272
	ds_read_b128 v[192:195], v147 offset:55296
	ds_read_b128 v[198:201], v147 offset:56320
	global_load_lds_dwordx4 v[218:219], off
	v_lshl_add_u64 v[218:219], v[224:225], 0, s[10:11]
	s_mov_b32 m0, s62
	s_nop 0
	global_load_lds_dwordx4 v[218:219], off
	s_barrier
; DI float bflo(unsigned u) { return __uint_as_float(u << 16); }
; DI float bfhi(unsigned u) { return __uint_as_float(u & 0xffff0000u); }
; #define PG8_STAGE(bufoff, gbase, voff) do { _Pragma("unroll") for (int _i = 0; _i < 2; ++_i) \
;         __builtin_amdgcn_global_load_lds((const unsigned*)((const char*)(gbase) + (voff)[_i]), (LAS unsigned*)(lds + (bufoff) + ldsw + _i * 8192), 16, 0, 0); } while (0)
; #define PG8_MMA(ai, bj, At, Bt) do { __builtin_amdgcn_s_setprio(1); _Pragma("unroll") for (int m = 0; m < 4; ++m) _Pragma("unroll") for (int n = 0; n < 2; ++n) _Pragma("unroll") for (int k = 0; k < 2; ++k) \
;         acc[ai][bj][m][n] = __builtin_amdgcn_mfma_f32_16x16x32_bf16(Bt[n][k], At[m][k], acc[ai][bj][m][n], 0, 0, 0); __builtin_amdgcn_s_setprio(0); } while (0)
; #define PG8_WAIT_V(n) asm volatile("s_waitcnt vmcnt(" #n ")" ::: "memory")
; #define PG8_WAIT_L(n) asm volatile("s_waitcnt lgkmcnt(" #n ")" ::: "memory")
; #define PG8_BAR __builtin_amdgcn_s_barrier()
; #define PG8_SCHED __builtin_amdgcn_sched_barrier(0)
;     DI void operator()(const f32x4 (&acc)[2][2][4][2], const Unit& u, int wr, int wc, int fr, int fq) const {
;         const int row0 = u.pm * BM + wr * 64 + fr, col0 = u.pn * BM + wc * 32 + 4 * fq;
; #pragma unroll
;         for (int ai = 0; ai < 2; ++ai)
; #pragma unroll
;             for (int m = 0; m < 4; ++m) { const size_t o = (size_t)(row0 + ai * HALF + m * 16) * 1024 + col0;
; #pragma unroll
;                 for (int bj = 0; bj < 2; ++bj)
; #pragma unroll
;                     for (int n = 0; n < 2; ++n) { const size_t oo = o + bj * HALF + n * 16; f32x4 rv;
;                         if (RES_BF16) { const u32x2 t = *(const u32x2*)((const bf16_t*)res + oo); rv = (f32x4){bflo(t.x), bfhi(t.x), bflo(t.y), bfhi(t.y)}; }
; template <class Epi, class Sched>
; DI void gemm_phase(LAS unsigned char* lds, const Gemm g, const Sched& S, const Epi& E) {
;     ...
;             PG8_BAR; PG8_WAIT_L(0); PG8_MMA(1, 0, At, B0); PG8_BAR; PG8_SCHED;
;             PG8_STAGE(PG8_SB(1, 1), b3 + hstep, voffB);
;             PG8_WAIT_V(6); PG8_BAR; PG8_MMA(1, 1, At, B1); PG8_BAR;
	s_waitcnt lgkmcnt(0)
	s_setprio 1
	s_waitcnt lgkmcnt(0)
	v_mfma_f32_16x16x32_bf16 v[62:65], v[140:143], v[168:171], v[62:65]
	v_mfma_f32_16x16x32_bf16 v[58:61], v[154:157], v[168:171], v[58:61]
	v_mfma_f32_16x16x32_bf16 v[46:49], v[140:143], v[176:179], v[46:49]
	v_mfma_f32_16x16x32_bf16 v[42:45], v[154:157], v[176:179], v[42:45]
	v_mfma_f32_16x16x32_bf16 v[30:33], v[140:143], v[184:187], v[30:33]
	v_mfma_f32_16x16x32_bf16 v[26:29], v[154:157], v[184:187], v[26:29]
	v_mfma_f32_16x16x32_bf16 v[14:17], v[140:143], v[192:195], v[14:17]
	v_mfma_f32_16x16x32_bf16 v[10:13], v[154:157], v[192:195], v[10:13]
	v_mfma_f32_16x16x32_bf16 v[62:65], v[150:153], v[172:175], v[62:65]
	v_mfma_f32_16x16x32_bf16 v[58:61], v[158:161], v[172:175], v[58:61]
	v_mfma_f32_16x16x32_bf16 v[46:49], v[150:153], v[180:183], v[46:49]
	v_mfma_f32_16x16x32_bf16 v[42:45], v[158:161], v[180:183], v[42:45]
	v_mfma_f32_16x16x32_bf16 v[30:33], v[150:153], v[188:191], v[30:33]
	v_mfma_f32_16x16x32_bf16 v[26:29], v[158:161], v[188:191], v[26:29]
	v_mfma_f32_16x16x32_bf16 v[14:17], v[150:153], v[198:201], v[14:17]
	v_mfma_f32_16x16x32_bf16 v[10:13], v[158:161], v[198:201], v[10:13]
	s_setprio 0
	s_barrier
	s_add_u32 s50, s50, 0x80080
	s_addc_u32 s51, s51, 0
	s_add_i32 s52, s52, s33
	v_lshl_add_u64 v[140:141], s[50:51], 0, v[132:133]
	s_mov_b32 m0, s52
	s_nop 0
	global_load_lds_dwordx4 v[140:141], off
	v_lshl_add_u64 v[140:141], s[50:51], 0, v[130:131]
	s_add_i32 m0, s52, 0x2000
	s_nop 0
	global_load_lds_dwordx4 v[140:141], off
	s_waitcnt vmcnt(6)
	s_barrier
	s_setprio 1
	v_mfma_f32_16x16x32_bf16 v[54:57], v[202:205], v[168:171], v[54:57]
	v_mfma_f32_16x16x32_bf16 v[50:53], v[210:213], v[168:171], v[50:53]
	v_mfma_f32_16x16x32_bf16 v[38:41], v[202:205], v[176:179], v[38:41]
	v_mfma_f32_16x16x32_bf16 v[34:37], v[210:213], v[176:179], v[34:37]
	v_mfma_f32_16x16x32_bf16 v[22:25], v[202:205], v[184:187], v[22:25]
	v_mfma_f32_16x16x32_bf16 v[18:21], v[210:213], v[184:187], v[18:21]
	v_mfma_f32_16x16x32_bf16 v[6:9], v[202:205], v[192:195], v[6:9]
	v_mfma_f32_16x16x32_bf16 v[2:5], v[210:213], v[192:195], v[2:5]
	v_mfma_f32_16x16x32_bf16 v[54:57], v[206:209], v[172:175], v[54:57]
	v_mfma_f32_16x16x32_bf16 v[50:53], v[214:217], v[172:175], v[50:53]
	v_mfma_f32_16x16x32_bf16 v[38:41], v[206:209], v[180:183], v[38:41]
	v_mfma_f32_16x16x32_bf16 v[34:37], v[214:217], v[180:183], v[34:37]
	v_mfma_f32_16x16x32_bf16 v[22:25], v[206:209], v[188:191], v[22:25]
	v_mfma_f32_16x16x32_bf16 v[18:21], v[214:217], v[188:191], v[18:21]
	v_mfma_f32_16x16x32_bf16 v[6:9], v[206:209], v[198:201], v[6:9]
	v_mfma_f32_16x16x32_bf16 v[2:5], v[214:217], v[198:201], v[2:5]
	s_setprio 0
	s_add_i32 s73, s73, 2
	s_add_u32 s42, s42, 0x100
	s_addc_u32 s43, s43, 0
	s_add_u32 s71, s71, 0x100
	s_addc_u32 s72, s72, 0
	s_cmp_gt_u32 s73, 29
	s_barrier
	s_cbranch_scc0 .LBB0_1523
	v_lshl_add_u32 v236, s56, 8, v144
	v_lshl_or_b32 v237, s84, 9, v149
	v_lshl_or_b32 v236, v236, 11, v237
	v_mov_b32_e32 v228, v236
	v_add_u32_e32 v229, 0x8000, v236
	v_add_u32_e32 v230, 0x10000, v236
	v_add_u32_e32 v231, 0x18000, v236
	v_add_u32_e32 v232, 0x40000, v236
	v_add_u32_e32 v233, 0x48000, v236
	v_add_u32_e32 v234, 0x50000, v236
	v_add_u32_e32 v235, 0x58000, v236
	v_and_b32_e32 v248, 63, v1
	v_lshrrev_b32_e32 v249, 3, v248
	v_and_b32_e32 v250, 3, v248
	v_lshl_or_b32 v250, v250, 4, v249
	v_lshlrev_b32_e32 v244, 2, v250
	v_add_u32_e32 v245, 32, v244
	v_and_b32_e32 v250, 0xffffffc0, v144
	v_add_u32_e32 v250, v250, v249
	v_lshl_add_u32 v250, s56, 8, v250
	v_mul_u32_u24_e32 v250, 0x800, v250
	v_and_b32_e32 v247, 0xffffffc0, v149
	v_lshl_or_b32 v247, s84, 9, v247
	v_and_b32_e32 v248, 7, v248
	v_lshl_add_u32 v247, v248, 3, v247
	v_add_u32_e32 v246, v250, v247
	s_mov_b32 s98, 0xf0f0f0f0
	s_mov_b32 s99, 0xf0f0f0f0
	s_and_b64 vcc, exec, s[40:41]
	s_mov_b32 s84, s65
	s_mov_b32 s56, s66
	global_load_dwordx2 v[140:141], v228, s[48:49]
	global_load_dwordx2 v[142:143], v228, s[48:49] offset:32
	global_load_dwordx2 v[150:151], v228, s[48:49] offset:256
	global_load_dwordx2 v[152:153], v228, s[48:49] offset:288
	global_load_dwordx2 v[154:155], v229, s[48:49]
	global_load_dwordx2 v[156:157], v229, s[48:49] offset:32
	global_load_dwordx2 v[158:159], v229, s[48:49] offset:256
	global_load_dwordx2 v[160:161], v229, s[48:49] offset:288
	global_load_dwordx2 v[168:169], v230, s[48:49]
	global_load_dwordx2 v[170:171], v230, s[48:49] offset:32
	global_load_dwordx2 v[172:173], v230, s[48:49] offset:256
	global_load_dwordx2 v[174:175], v230, s[48:49] offset:288
	global_load_dwordx2 v[176:177], v231, s[48:49]
	global_load_dwordx2 v[178:179], v231, s[48:49] offset:32
	global_load_dwordx2 v[180:181], v231, s[48:49] offset:256
	global_load_dwordx2 v[182:183], v231, s[48:49] offset:288
	global_load_dwordx2 v[184:185], v232, s[48:49]
	global_load_dwordx2 v[186:187], v232, s[48:49] offset:32
	global_load_dwordx2 v[188:189], v232, s[48:49] offset:256
	global_load_dwordx2 v[190:191], v232, s[48:49] offset:288
	global_load_dwordx2 v[192:193], v233, s[48:49]
	global_load_dwordx2 v[194:195], v233, s[48:49] offset:32
	global_load_dwordx2 v[198:199], v233, s[48:49] offset:256
	global_load_dwordx2 v[200:201], v233, s[48:49] offset:288
	global_load_dwordx2 v[202:203], v234, s[48:49]
	global_load_dwordx2 v[204:205], v234, s[48:49] offset:32
	global_load_dwordx2 v[206:207], v234, s[48:49] offset:256
	global_load_dwordx2 v[208:209], v234, s[48:49] offset:288
	global_load_dwordx2 v[210:211], v235, s[48:49]
	global_load_dwordx2 v[212:213], v235, s[48:49] offset:32
	global_load_dwordx2 v[214:215], v235, s[48:49] offset:256
	global_load_dwordx2 v[216:217], v235, s[48:49] offset:288
	s_waitcnt vmcnt(28)
; DI unsigned pk_bf16(float a, float b) { f32x2 v = {a, b}; bf2_t r = __builtin_convertvector(v, bf2_t); return __builtin_bit_cast(unsigned, r); }
; DI float bflo(unsigned u) { return __uint_as_float(u << 16); }
; DI float bfhi(unsigned u) { return __uint_as_float(u & 0xffff0000u); }
;     DI void operator()(const f32x4 (&acc)[2][2][4][2], const Unit& u, int wr, int wc, int fr, int fq) const {
;     ...
;             for (int m = 0; m < 4; ++m) { const size_t o = (size_t)(row0 + ai * HALF + m * 16) * 1024 + col0;
; #pragma unroll
;                 for (int bj = 0; bj < 2; ++bj)
; #pragma unroll
;                     for (int n = 0; n < 2; ++n) { const size_t oo = o + bj * HALF + n * 16; f32x4 rv;
;                         if (RES_BF16) { const u32x2 t = *(const u32x2*)((const bf16_t*)res + oo); rv = (f32x4){bflo(t.x), bfhi(t.x), bflo(t.y), bfhi(t.y)}; }
;                         else rv = *(const f32x4*)((const float*)res + oo);
;                         const f32x4 v = acc[ai][bj][m][n] + rv; u32x2 w; w.x = pk_bf16(v.x, v.y); w.y = pk_bf16(v.z, v.w);
;                         *(u32x2*)(O + oo) = w; } }
	v_lshlrev_b32_e32 v226, 16, v141
	v_and_b32_e32 v227, 0xffff0000, v141
	v_and_b32_e32 v141, 0xffff0000, v140
	v_lshlrev_b32_e32 v140, 16, v140
	v_pk_add_f32 v[128:129], v[128:129], v[226:227]
	v_pk_add_f32 v[126:127], v[126:127], v[140:141]
	v_lshlrev_b32_e32 v240, 16, v143
	v_and_b32_e32 v241, 0xffff0000, v143
	v_and_b32_e32 v143, 0xffff0000, v142
	v_lshlrev_b32_e32 v142, 16, v142
	v_pk_add_f32 v[124:125], v[124:125], v[240:241]
	v_pk_add_f32 v[122:123], v[122:123], v[142:143]
	v_lshlrev_b32_e32 v226, 16, v151
	v_and_b32_e32 v227, 0xffff0000, v151
	v_and_b32_e32 v151, 0xffff0000, v150
	v_lshlrev_b32_e32 v150, 16, v150
	v_pk_add_f32 v[120:121], v[120:121], v[226:227]
	v_pk_add_f32 v[118:119], v[118:119], v[150:151]
	v_lshlrev_b32_e32 v240, 16, v153
	v_and_b32_e32 v241, 0xffff0000, v153
	v_and_b32_e32 v153, 0xffff0000, v152
	v_lshlrev_b32_e32 v152, 16, v152
	v_pk_add_f32 v[116:117], v[116:117], v[240:241]
	v_pk_add_f32 v[114:115], v[114:115], v[152:153]
	v_cvt_pk_bf16_f32 v126, v126, v127
	v_cvt_pk_bf16_f32 v127, v128, v129
	v_cvt_pk_bf16_f32 v122, v122, v123
	v_cvt_pk_bf16_f32 v123, v124, v125
	v_cvt_pk_bf16_f32 v118, v118, v119
	v_cvt_pk_bf16_f32 v119, v120, v121
	v_cvt_pk_bf16_f32 v114, v114, v115
	v_cvt_pk_bf16_f32 v115, v116, v117
	ds_bpermute_b32 v140, v244, v126
	ds_bpermute_b32 v141, v244, v127
	ds_bpermute_b32 v142, v244, v122
	ds_bpermute_b32 v143, v244, v123
	ds_bpermute_b32 v150, v245, v126
	ds_bpermute_b32 v151, v245, v127
	ds_bpermute_b32 v152, v245, v122
	ds_bpermute_b32 v153, v245, v123
	s_waitcnt lgkmcnt(0)
	v_cndmask_b32_e64 v140, v140, v142, s[98:99]
	v_cndmask_b32_e64 v141, v141, v143, s[98:99]
	v_mov_b32_e32 v142, v246
	global_store_dwordx2 v142, v[140:141], s[8:9]
	v_cndmask_b32_e64 v150, v150, v152, s[98:99]
	v_cndmask_b32_e64 v151, v151, v153, s[98:99]
	v_add_u32_e32 v152, 0x4000, v246
	global_store_dwordx2 v152, v[150:151], s[8:9]
	ds_bpermute_b32 v140, v244, v118
	ds_bpermute_b32 v141, v244, v119
	ds_bpermute_b32 v142, v244, v114
	ds_bpermute_b32 v143, v244, v115
	ds_bpermute_b32 v150, v245, v118
	ds_bpermute_b32 v151, v245, v119
	ds_bpermute_b32 v152, v245, v114
	ds_bpermute_b32 v153, v245, v115
	s_waitcnt lgkmcnt(0)
	v_cndmask_b32_e64 v140, v140, v142, s[98:99]
	v_cndmask_b32_e64 v141, v141, v143, s[98:99]
	v_mov_b32_e32 v142, v246
	global_store_dwordx2 v142, v[140:141], s[8:9] offset:256
	v_cndmask_b32_e64 v150, v150, v152, s[98:99]
	v_cndmask_b32_e64 v151, v151, v153, s[98:99]
	v_add_u32_e32 v152, 0x4000, v246
	global_store_dwordx2 v152, v[150:151], s[8:9] offset:256
	s_waitcnt vmcnt(28)
	v_lshlrev_b32_e32 v226, 16, v155
	v_and_b32_e32 v227, 0xffff0000, v155
	v_and_b32_e32 v155, 0xffff0000, v154
	v_lshlrev_b32_e32 v154, 16, v154
	v_pk_add_f32 v[112:113], v[112:113], v[226:227]
	v_pk_add_f32 v[110:111], v[110:111], v[154:155]
	v_lshlrev_b32_e32 v240, 16, v157
	v_and_b32_e32 v241, 0xffff0000, v157
	v_and_b32_e32 v157, 0xffff0000, v156
	v_lshlrev_b32_e32 v156, 16, v156
	v_pk_add_f32 v[108:109], v[108:109], v[240:241]
	v_pk_add_f32 v[106:107], v[106:107], v[156:157]
	v_lshlrev_b32_e32 v226, 16, v159
	v_and_b32_e32 v227, 0xffff0000, v159
	v_and_b32_e32 v159, 0xffff0000, v158
	v_lshlrev_b32_e32 v158, 16, v158
	v_pk_add_f32 v[104:105], v[104:105], v[226:227]
	v_pk_add_f32 v[102:103], v[102:103], v[158:159]
	v_lshlrev_b32_e32 v240, 16, v161
	v_and_b32_e32 v241, 0xffff0000, v161
	v_and_b32_e32 v161, 0xffff0000, v160
	v_lshlrev_b32_e32 v160, 16, v160
	v_pk_add_f32 v[100:101], v[100:101], v[240:241]
	v_pk_add_f32 v[98:99], v[98:99], v[160:161]
	v_cvt_pk_bf16_f32 v110, v110, v111
	v_cvt_pk_bf16_f32 v111, v112, v113
	v_cvt_pk_bf16_f32 v106, v106, v107
	v_cvt_pk_bf16_f32 v107, v108, v109
	v_cvt_pk_bf16_f32 v102, v102, v103
	v_cvt_pk_bf16_f32 v103, v104, v105
	v_cvt_pk_bf16_f32 v98, v98, v99
	v_cvt_pk_bf16_f32 v99, v100, v101
	ds_bpermute_b32 v154, v244, v110
	ds_bpermute_b32 v155, v244, v111
	ds_bpermute_b32 v156, v244, v106
	ds_bpermute_b32 v157, v244, v107
	ds_bpermute_b32 v158, v245, v110
	ds_bpermute_b32 v159, v245, v111
	ds_bpermute_b32 v160, v245, v106
	ds_bpermute_b32 v161, v245, v107
	s_waitcnt lgkmcnt(0)
	v_cndmask_b32_e64 v154, v154, v156, s[98:99]
	v_cndmask_b32_e64 v155, v155, v157, s[98:99]
	v_add_u32_e32 v156, 0x8000, v246
	global_store_dwordx2 v156, v[154:155], s[8:9]
	v_cndmask_b32_e64 v158, v158, v160, s[98:99]
	v_cndmask_b32_e64 v159, v159, v161, s[98:99]
	v_add_u32_e32 v160, 0xc000, v246
	global_store_dwordx2 v160, v[158:159], s[8:9]
	ds_bpermute_b32 v154, v244, v102
	ds_bpermute_b32 v155, v244, v103
	ds_bpermute_b32 v156, v244, v98
	ds_bpermute_b32 v157, v244, v99
	ds_bpermute_b32 v158, v245, v102
	ds_bpermute_b32 v159, v245, v103
	ds_bpermute_b32 v160, v245, v98
	ds_bpermute_b32 v161, v245, v99
	s_waitcnt lgkmcnt(0)
	v_cndmask_b32_e64 v154, v154, v156, s[98:99]
	v_cndmask_b32_e64 v155, v155, v157, s[98:99]
	v_add_u32_e32 v156, 0x8000, v246
	global_store_dwordx2 v156, v[154:155], s[8:9] offset:256
	v_cndmask_b32_e64 v158, v158, v160, s[98:99]
	v_cndmask_b32_e64 v159, v159, v161, s[98:99]
	v_add_u32_e32 v160, 0xc000, v246
	global_store_dwordx2 v160, v[158:159], s[8:9] offset:256
	s_waitcnt vmcnt(28)
; DI unsigned pk_bf16(float a, float b) { f32x2 v = {a, b}; bf2_t r = __builtin_convertvector(v, bf2_t); return __builtin_bit_cast(unsigned, r); }
; DI float bflo(unsigned u) { return __uint_as_float(u << 16); }
; DI float bfhi(unsigned u) { return __uint_as_float(u & 0xffff0000u); }
;     DI void operator()(const f32x4 (&acc)[2][2][4][2], const Unit& u, int wr, int wc, int fr, int fq) const {
;     ...
;             for (int m = 0; m < 4; ++m) { const size_t o = (size_t)(row0 + ai * HALF + m * 16) * 1024 + col0;
; #pragma unroll
;                 for (int bj = 0; bj < 2; ++bj)
; #pragma unroll
;                     for (int n = 0; n < 2; ++n) { const size_t oo = o + bj * HALF + n * 16; f32x4 rv;
;                         if (RES_BF16) { const u32x2 t = *(const u32x2*)((const bf16_t*)res + oo); rv = (f32x4){bflo(t.x), bfhi(t.x), bflo(t.y), bfhi(t.y)}; }
;                         else rv = *(const f32x4*)((const float*)res + oo);
;                         const f32x4 v = acc[ai][bj][m][n] + rv; u32x2 w; w.x = pk_bf16(v.x, v.y); w.y = pk_bf16(v.z, v.w);
;                         *(u32x2*)(O + oo) = w; } }
	v_lshlrev_b32_e32 v226, 16, v169
	v_and_b32_e32 v227, 0xffff0000, v169
	v_and_b32_e32 v169, 0xffff0000, v168
	v_lshlrev_b32_e32 v168, 16, v168
	v_pk_add_f32 v[96:97], v[96:97], v[226:227]
	v_pk_add_f32 v[94:95], v[94:95], v[168:169]
	v_lshlrev_b32_e32 v240, 16, v171
	v_and_b32_e32 v241, 0xffff0000, v171
	v_and_b32_e32 v171, 0xffff0000, v170
	v_lshlrev_b32_e32 v170, 16, v170
	v_pk_add_f32 v[92:93], v[92:93], v[240:241]
	v_pk_add_f32 v[90:91], v[90:91], v[170:171]
	v_lshlrev_b32_e32 v226, 16, v173
	v_and_b32_e32 v227, 0xffff0000, v173
	v_and_b32_e32 v173, 0xffff0000, v172
	v_lshlrev_b32_e32 v172, 16, v172
	v_pk_add_f32 v[88:89], v[88:89], v[226:227]
	v_pk_add_f32 v[86:87], v[86:87], v[172:173]
	v_lshlrev_b32_e32 v240, 16, v175
	v_and_b32_e32 v241, 0xffff0000, v175
	v_and_b32_e32 v175, 0xffff0000, v174
	v_lshlrev_b32_e32 v174, 16, v174
	v_pk_add_f32 v[84:85], v[84:85], v[240:241]
	v_pk_add_f32 v[82:83], v[82:83], v[174:175]
	v_cvt_pk_bf16_f32 v94, v94, v95
	v_cvt_pk_bf16_f32 v95, v96, v97
	v_cvt_pk_bf16_f32 v90, v90, v91
	v_cvt_pk_bf16_f32 v91, v92, v93
	v_cvt_pk_bf16_f32 v86, v86, v87
	v_cvt_pk_bf16_f32 v87, v88, v89
	v_cvt_pk_bf16_f32 v82, v82, v83
	v_cvt_pk_bf16_f32 v83, v84, v85
	ds_bpermute_b32 v168, v244, v94
	ds_bpermute_b32 v169, v244, v95
	ds_bpermute_b32 v170, v244, v90
	ds_bpermute_b32 v171, v244, v91
	ds_bpermute_b32 v172, v245, v94
	ds_bpermute_b32 v173, v245, v95
	ds_bpermute_b32 v174, v245, v90
	ds_bpermute_b32 v175, v245, v91
	s_waitcnt lgkmcnt(0)
	v_cndmask_b32_e64 v168, v168, v170, s[98:99]
	v_cndmask_b32_e64 v169, v169, v171, s[98:99]
	v_add_u32_e32 v170, 0x10000, v246
	global_store_dwordx2 v170, v[168:169], s[8:9]
	v_cndmask_b32_e64 v172, v172, v174, s[98:99]
	v_cndmask_b32_e64 v173, v173, v175, s[98:99]
	v_add_u32_e32 v174, 0x14000, v246
	global_store_dwordx2 v174, v[172:173], s[8:9]
	ds_bpermute_b32 v168, v244, v86
	ds_bpermute_b32 v169, v244, v87
	ds_bpermute_b32 v170, v244, v82
	ds_bpermute_b32 v171, v244, v83
	ds_bpermute_b32 v172, v245, v86
	ds_bpermute_b32 v173, v245, v87
	ds_bpermute_b32 v174, v245, v82
	ds_bpermute_b32 v175, v245, v83
	s_waitcnt lgkmcnt(0)
	v_cndmask_b32_e64 v168, v168, v170, s[98:99]
	v_cndmask_b32_e64 v169, v169, v171, s[98:99]
	v_add_u32_e32 v170, 0x10000, v246
	global_store_dwordx2 v170, v[168:169], s[8:9] offset:256
	v_cndmask_b32_e64 v172, v172, v174, s[98:99]
	v_cndmask_b32_e64 v173, v173, v175, s[98:99]
	v_add_u32_e32 v174, 0x14000, v246
	global_store_dwordx2 v174, v[172:173], s[8:9] offset:256
	s_waitcnt vmcnt(28)
	v_lshlrev_b32_e32 v226, 16, v177
	v_and_b32_e32 v227, 0xffff0000, v177
	v_and_b32_e32 v177, 0xffff0000, v176
	v_lshlrev_b32_e32 v176, 16, v176
	v_pk_add_f32 v[80:81], v[80:81], v[226:227]
	v_pk_add_f32 v[78:79], v[78:79], v[176:177]
	v_lshlrev_b32_e32 v240, 16, v179
	v_and_b32_e32 v241, 0xffff0000, v179
	v_and_b32_e32 v179, 0xffff0000, v178
	v_lshlrev_b32_e32 v178, 16, v178
	v_pk_add_f32 v[76:77], v[76:77], v[240:241]
	v_pk_add_f32 v[74:75], v[74:75], v[178:179]
	v_lshlrev_b32_e32 v226, 16, v181
	v_and_b32_e32 v227, 0xffff0000, v181
	v_and_b32_e32 v181, 0xffff0000, v180
	v_lshlrev_b32_e32 v180, 16, v180
	v_pk_add_f32 v[72:73], v[72:73], v[226:227]
	v_pk_add_f32 v[70:71], v[70:71], v[180:181]
	v_lshlrev_b32_e32 v240, 16, v183
	v_and_b32_e32 v241, 0xffff0000, v183
	v_and_b32_e32 v183, 0xffff0000, v182
	v_lshlrev_b32_e32 v182, 16, v182
	v_pk_add_f32 v[68:69], v[68:69], v[240:241]
	v_pk_add_f32 v[66:67], v[66:67], v[182:183]
	v_cvt_pk_bf16_f32 v78, v78, v79
	v_cvt_pk_bf16_f32 v79, v80, v81
	v_cvt_pk_bf16_f32 v74, v74, v75
	v_cvt_pk_bf16_f32 v75, v76, v77
	v_cvt_pk_bf16_f32 v70, v70, v71
	v_cvt_pk_bf16_f32 v71, v72, v73
	v_cvt_pk_bf16_f32 v66, v66, v67
	v_cvt_pk_bf16_f32 v67, v68, v69
	ds_bpermute_b32 v176, v244, v78
	ds_bpermute_b32 v177, v244, v79
	ds_bpermute_b32 v178, v244, v74
	ds_bpermute_b32 v179, v244, v75
	ds_bpermute_b32 v180, v245, v78
	ds_bpermute_b32 v181, v245, v79
	ds_bpermute_b32 v182, v245, v74
	ds_bpermute_b32 v183, v245, v75
	s_waitcnt lgkmcnt(0)
	v_cndmask_b32_e64 v176, v176, v178, s[98:99]
	v_cndmask_b32_e64 v177, v177, v179, s[98:99]
	v_add_u32_e32 v178, 0x18000, v246
	global_store_dwordx2 v178, v[176:177], s[8:9]
	v_cndmask_b32_e64 v180, v180, v182, s[98:99]
	v_cndmask_b32_e64 v181, v181, v183, s[98:99]
	v_add_u32_e32 v182, 0x1c000, v246
	global_store_dwordx2 v182, v[180:181], s[8:9]
	ds_bpermute_b32 v176, v244, v70
	ds_bpermute_b32 v177, v244, v71
	ds_bpermute_b32 v178, v244, v66
	ds_bpermute_b32 v179, v244, v67
	ds_bpermute_b32 v180, v245, v70
	ds_bpermute_b32 v181, v245, v71
	ds_bpermute_b32 v182, v245, v66
	ds_bpermute_b32 v183, v245, v67
	s_waitcnt lgkmcnt(0)
	v_cndmask_b32_e64 v176, v176, v178, s[98:99]
	v_cndmask_b32_e64 v177, v177, v179, s[98:99]
	v_add_u32_e32 v178, 0x18000, v246
	global_store_dwordx2 v178, v[176:177], s[8:9] offset:256
	v_cndmask_b32_e64 v180, v180, v182, s[98:99]
	v_cndmask_b32_e64 v181, v181, v183, s[98:99]
	v_add_u32_e32 v182, 0x1c000, v246
	global_store_dwordx2 v182, v[180:181], s[8:9] offset:256
	s_waitcnt vmcnt(28)
; DI unsigned pk_bf16(float a, float b) { f32x2 v = {a, b}; bf2_t r = __builtin_convertvector(v, bf2_t); return __builtin_bit_cast(unsigned, r); }
; DI float bflo(unsigned u) { return __uint_as_float(u << 16); }
; DI float bfhi(unsigned u) { return __uint_as_float(u & 0xffff0000u); }
;     DI void operator()(const f32x4 (&acc)[2][2][4][2], const Unit& u, int wr, int wc, int fr, int fq) const {
;     ...
;             for (int m = 0; m < 4; ++m) { const size_t o = (size_t)(row0 + ai * HALF + m * 16) * 1024 + col0;
; #pragma unroll
;                 for (int bj = 0; bj < 2; ++bj)
; #pragma unroll
;                     for (int n = 0; n < 2; ++n) { const size_t oo = o + bj * HALF + n * 16; f32x4 rv;
;                         if (RES_BF16) { const u32x2 t = *(const u32x2*)((const bf16_t*)res + oo); rv = (f32x4){bflo(t.x), bfhi(t.x), bflo(t.y), bfhi(t.y)}; }
;                         else rv = *(const f32x4*)((const float*)res + oo);
;                         const f32x4 v = acc[ai][bj][m][n] + rv; u32x2 w; w.x = pk_bf16(v.x, v.y); w.y = pk_bf16(v.z, v.w);
;                         *(u32x2*)(O + oo) = w; } }
	v_lshlrev_b32_e32 v226, 16, v185
	v_and_b32_e32 v227, 0xffff0000, v185
	v_and_b32_e32 v185, 0xffff0000, v184
	v_lshlrev_b32_e32 v184, 16, v184
	v_pk_add_f32 v[64:65], v[64:65], v[226:227]
	v_pk_add_f32 v[62:63], v[62:63], v[184:185]
	v_lshlrev_b32_e32 v240, 16, v187
	v_and_b32_e32 v241, 0xffff0000, v187
	v_and_b32_e32 v187, 0xffff0000, v186
	v_lshlrev_b32_e32 v186, 16, v186
	v_pk_add_f32 v[60:61], v[60:61], v[240:241]
	v_pk_add_f32 v[58:59], v[58:59], v[186:187]
	v_lshlrev_b32_e32 v226, 16, v189
	v_and_b32_e32 v227, 0xffff0000, v189
	v_and_b32_e32 v189, 0xffff0000, v188
	v_lshlrev_b32_e32 v188, 16, v188
	v_pk_add_f32 v[56:57], v[56:57], v[226:227]
	v_pk_add_f32 v[54:55], v[54:55], v[188:189]
	v_lshlrev_b32_e32 v240, 16, v191
	v_and_b32_e32 v241, 0xffff0000, v191
	v_and_b32_e32 v191, 0xffff0000, v190
	v_lshlrev_b32_e32 v190, 16, v190
	v_pk_add_f32 v[52:53], v[52:53], v[240:241]
	v_pk_add_f32 v[50:51], v[50:51], v[190:191]
	v_cvt_pk_bf16_f32 v62, v62, v63
	v_cvt_pk_bf16_f32 v63, v64, v65
	v_cvt_pk_bf16_f32 v58, v58, v59
	v_cvt_pk_bf16_f32 v59, v60, v61
	v_cvt_pk_bf16_f32 v54, v54, v55
	v_cvt_pk_bf16_f32 v55, v56, v57
	v_cvt_pk_bf16_f32 v50, v50, v51
	v_cvt_pk_bf16_f32 v51, v52, v53
	ds_bpermute_b32 v184, v244, v62
	ds_bpermute_b32 v185, v244, v63
	ds_bpermute_b32 v186, v244, v58
	ds_bpermute_b32 v187, v244, v59
	ds_bpermute_b32 v188, v245, v62
	ds_bpermute_b32 v189, v245, v63
	ds_bpermute_b32 v190, v245, v58
	ds_bpermute_b32 v191, v245, v59
	s_waitcnt lgkmcnt(0)
	v_cndmask_b32_e64 v184, v184, v186, s[98:99]
	v_cndmask_b32_e64 v185, v185, v187, s[98:99]
	v_add_u32_e32 v186, 0x40000, v246
	global_store_dwordx2 v186, v[184:185], s[8:9]
	v_cndmask_b32_e64 v188, v188, v190, s[98:99]
	v_cndmask_b32_e64 v189, v189, v191, s[98:99]
	v_add_u32_e32 v190, 0x44000, v246
	global_store_dwordx2 v190, v[188:189], s[8:9]
	ds_bpermute_b32 v184, v244, v54
	ds_bpermute_b32 v185, v244, v55
	ds_bpermute_b32 v186, v244, v50
	ds_bpermute_b32 v187, v244, v51
	ds_bpermute_b32 v188, v245, v54
	ds_bpermute_b32 v189, v245, v55
	ds_bpermute_b32 v190, v245, v50
	ds_bpermute_b32 v191, v245, v51
	s_waitcnt lgkmcnt(0)
	v_cndmask_b32_e64 v184, v184, v186, s[98:99]
	v_cndmask_b32_e64 v185, v185, v187, s[98:99]
	v_add_u32_e32 v186, 0x40000, v246
	global_store_dwordx2 v186, v[184:185], s[8:9] offset:256
	v_cndmask_b32_e64 v188, v188, v190, s[98:99]
	v_cndmask_b32_e64 v189, v189, v191, s[98:99]
	v_add_u32_e32 v190, 0x44000, v246
	global_store_dwordx2 v190, v[188:189], s[8:9] offset:256
	s_waitcnt vmcnt(28)
	v_lshlrev_b32_e32 v226, 16, v193
	v_and_b32_e32 v227, 0xffff0000, v193
	v_and_b32_e32 v193, 0xffff0000, v192
	v_lshlrev_b32_e32 v192, 16, v192
	v_pk_add_f32 v[48:49], v[48:49], v[226:227]
	v_pk_add_f32 v[46:47], v[46:47], v[192:193]
	v_lshlrev_b32_e32 v240, 16, v195
	v_and_b32_e32 v241, 0xffff0000, v195
	v_and_b32_e32 v195, 0xffff0000, v194
	v_lshlrev_b32_e32 v194, 16, v194
	v_pk_add_f32 v[44:45], v[44:45], v[240:241]
	v_pk_add_f32 v[42:43], v[42:43], v[194:195]
	v_lshlrev_b32_e32 v226, 16, v199
	v_and_b32_e32 v227, 0xffff0000, v199
	v_and_b32_e32 v199, 0xffff0000, v198
	v_lshlrev_b32_e32 v198, 16, v198
	v_pk_add_f32 v[40:41], v[40:41], v[226:227]
	v_pk_add_f32 v[38:39], v[38:39], v[198:199]
	v_lshlrev_b32_e32 v240, 16, v201
	v_and_b32_e32 v241, 0xffff0000, v201
	v_and_b32_e32 v201, 0xffff0000, v200
	v_lshlrev_b32_e32 v200, 16, v200
	v_pk_add_f32 v[36:37], v[36:37], v[240:241]
	v_pk_add_f32 v[34:35], v[34:35], v[200:201]
	v_cvt_pk_bf16_f32 v46, v46, v47
	v_cvt_pk_bf16_f32 v47, v48, v49
	v_cvt_pk_bf16_f32 v42, v42, v43
	v_cvt_pk_bf16_f32 v43, v44, v45
	v_cvt_pk_bf16_f32 v38, v38, v39
	v_cvt_pk_bf16_f32 v39, v40, v41
	v_cvt_pk_bf16_f32 v34, v34, v35
	v_cvt_pk_bf16_f32 v35, v36, v37
	ds_bpermute_b32 v192, v244, v46
	ds_bpermute_b32 v193, v244, v47
	ds_bpermute_b32 v194, v244, v42
	ds_bpermute_b32 v195, v244, v43
	ds_bpermute_b32 v198, v245, v46
	ds_bpermute_b32 v199, v245, v47
	ds_bpermute_b32 v200, v245, v42
	ds_bpermute_b32 v201, v245, v43
	s_waitcnt lgkmcnt(0)
	v_cndmask_b32_e64 v192, v192, v194, s[98:99]
	v_cndmask_b32_e64 v193, v193, v195, s[98:99]
	v_add_u32_e32 v194, 0x48000, v246
	global_store_dwordx2 v194, v[192:193], s[8:9]
	v_cndmask_b32_e64 v198, v198, v200, s[98:99]
	v_cndmask_b32_e64 v199, v199, v201, s[98:99]
	v_add_u32_e32 v200, 0x4c000, v246
	global_store_dwordx2 v200, v[198:199], s[8:9]
	ds_bpermute_b32 v192, v244, v38
	ds_bpermute_b32 v193, v244, v39
	ds_bpermute_b32 v194, v244, v34
	ds_bpermute_b32 v195, v244, v35
	ds_bpermute_b32 v198, v245, v38
	ds_bpermute_b32 v199, v245, v39
	ds_bpermute_b32 v200, v245, v34
	ds_bpermute_b32 v201, v245, v35
	s_waitcnt lgkmcnt(0)
	v_cndmask_b32_e64 v192, v192, v194, s[98:99]
	v_cndmask_b32_e64 v193, v193, v195, s[98:99]
	v_add_u32_e32 v194, 0x48000, v246
	global_store_dwordx2 v194, v[192:193], s[8:9] offset:256
	v_cndmask_b32_e64 v198, v198, v200, s[98:99]
	v_cndmask_b32_e64 v199, v199, v201, s[98:99]
	v_add_u32_e32 v200, 0x4c000, v246
	global_store_dwordx2 v200, v[198:199], s[8:9] offset:256
	s_waitcnt vmcnt(28)
; DI unsigned pk_bf16(float a, float b) { f32x2 v = {a, b}; bf2_t r = __builtin_convertvector(v, bf2_t); return __builtin_bit_cast(unsigned, r); }
; DI float bflo(unsigned u) { return __uint_as_float(u << 16); }
; DI float bfhi(unsigned u) { return __uint_as_float(u & 0xffff0000u); }
; #define PG8_WAIT_V(n) asm volatile("s_waitcnt vmcnt(" #n ")" ::: "memory")
; #define PG8_BAR __builtin_amdgcn_s_barrier()
;     DI void operator()(const f32x4 (&acc)[2][2][4][2], const Unit& u, int wr, int wc, int fr, int fq) const {
;     ...
;             for (int m = 0; m < 4; ++m) { const size_t o = (size_t)(row0 + ai * HALF + m * 16) * 1024 + col0;
; #pragma unroll
;                 for (int bj = 0; bj < 2; ++bj)
; #pragma unroll
;                     for (int n = 0; n < 2; ++n) { const size_t oo = o + bj * HALF + n * 16; f32x4 rv;
;                         if (RES_BF16) { const u32x2 t = *(const u32x2*)((const bf16_t*)res + oo); rv = (f32x4){bflo(t.x), bfhi(t.x), bflo(t.y), bfhi(t.y)}; }
;                         else rv = *(const f32x4*)((const float*)res + oo);
;                         const f32x4 v = acc[ai][bj][m][n] + rv; u32x2 w; w.x = pk_bf16(v.x, v.y); w.y = pk_bf16(v.z, v.w);
;                         *(u32x2*)(O + oo) = w; } }
; template <class Epi, class Sched>
; DI void gemm_phase(LAS unsigned char* lds, const Gemm g, const Sched& S, const Epi& E) {
;     ...
;         if (!has_next) break;
; #pragma unroll
;         for (int a = 0; a < 2; ++a)
; #pragma unroll
;             for (int b = 0; b < 2; ++b)
; #pragma unroll
;                 for (int m = 0; m < 4; ++m)
; #pragma unroll
;                     for (int n = 0; n < 2; ++n) acc[a][b][m][n] = (f32x4){0.f, 0.f, 0.f, 0.f};
;         cur = nxt; cA = nA; cB = nB; ++ui;
;     }
;     PG8_WAIT_V(0);
;     if (wr == 0) PG8_BAR;
	v_lshlrev_b32_e32 v226, 16, v203
	v_and_b32_e32 v227, 0xffff0000, v203
	v_and_b32_e32 v203, 0xffff0000, v202
	v_lshlrev_b32_e32 v202, 16, v202
	v_pk_add_f32 v[32:33], v[32:33], v[226:227]
	v_pk_add_f32 v[30:31], v[30:31], v[202:203]
	v_lshlrev_b32_e32 v240, 16, v205
	v_and_b32_e32 v241, 0xffff0000, v205
	v_and_b32_e32 v205, 0xffff0000, v204
	v_lshlrev_b32_e32 v204, 16, v204
	v_pk_add_f32 v[28:29], v[28:29], v[240:241]
	v_pk_add_f32 v[26:27], v[26:27], v[204:205]
	v_lshlrev_b32_e32 v226, 16, v207
	v_and_b32_e32 v227, 0xffff0000, v207
	v_and_b32_e32 v207, 0xffff0000, v206
	v_lshlrev_b32_e32 v206, 16, v206
	v_pk_add_f32 v[24:25], v[24:25], v[226:227]
	v_pk_add_f32 v[22:23], v[22:23], v[206:207]
	v_lshlrev_b32_e32 v240, 16, v209
	v_and_b32_e32 v241, 0xffff0000, v209
	v_and_b32_e32 v209, 0xffff0000, v208
	v_lshlrev_b32_e32 v208, 16, v208
	v_pk_add_f32 v[20:21], v[20:21], v[240:241]
	v_pk_add_f32 v[18:19], v[18:19], v[208:209]
	v_cvt_pk_bf16_f32 v30, v30, v31
	v_cvt_pk_bf16_f32 v31, v32, v33
	v_cvt_pk_bf16_f32 v26, v26, v27
	v_cvt_pk_bf16_f32 v27, v28, v29
	v_cvt_pk_bf16_f32 v22, v22, v23
	v_cvt_pk_bf16_f32 v23, v24, v25
	v_cvt_pk_bf16_f32 v18, v18, v19
	v_cvt_pk_bf16_f32 v19, v20, v21
	ds_bpermute_b32 v202, v244, v30
	ds_bpermute_b32 v203, v244, v31
	ds_bpermute_b32 v204, v244, v26
	ds_bpermute_b32 v205, v244, v27
	ds_bpermute_b32 v206, v245, v30
	ds_bpermute_b32 v207, v245, v31
	ds_bpermute_b32 v208, v245, v26
	ds_bpermute_b32 v209, v245, v27
	s_waitcnt lgkmcnt(0)
	v_cndmask_b32_e64 v202, v202, v204, s[98:99]
	v_cndmask_b32_e64 v203, v203, v205, s[98:99]
	v_add_u32_e32 v204, 0x50000, v246
	global_store_dwordx2 v204, v[202:203], s[8:9]
	v_cndmask_b32_e64 v206, v206, v208, s[98:99]
	v_cndmask_b32_e64 v207, v207, v209, s[98:99]
	v_add_u32_e32 v208, 0x54000, v246
	global_store_dwordx2 v208, v[206:207], s[8:9]
	ds_bpermute_b32 v202, v244, v22
	ds_bpermute_b32 v203, v244, v23
	ds_bpermute_b32 v204, v244, v18
	ds_bpermute_b32 v205, v244, v19
	ds_bpermute_b32 v206, v245, v22
	ds_bpermute_b32 v207, v245, v23
	ds_bpermute_b32 v208, v245, v18
	ds_bpermute_b32 v209, v245, v19
	s_waitcnt lgkmcnt(0)
	v_cndmask_b32_e64 v202, v202, v204, s[98:99]
	v_cndmask_b32_e64 v203, v203, v205, s[98:99]
	v_add_u32_e32 v204, 0x50000, v246
	global_store_dwordx2 v204, v[202:203], s[8:9] offset:256
	v_cndmask_b32_e64 v206, v206, v208, s[98:99]
	v_cndmask_b32_e64 v207, v207, v209, s[98:99]
	v_add_u32_e32 v208, 0x54000, v246
	global_store_dwordx2 v208, v[206:207], s[8:9] offset:256
	s_waitcnt vmcnt(28)
	v_lshlrev_b32_e32 v226, 16, v211
	v_and_b32_e32 v227, 0xffff0000, v211
	v_and_b32_e32 v211, 0xffff0000, v210
	v_lshlrev_b32_e32 v210, 16, v210
	v_pk_add_f32 v[16:17], v[16:17], v[226:227]
	v_pk_add_f32 v[14:15], v[14:15], v[210:211]
	v_lshlrev_b32_e32 v240, 16, v213
	v_and_b32_e32 v241, 0xffff0000, v213
	v_and_b32_e32 v213, 0xffff0000, v212
	v_lshlrev_b32_e32 v212, 16, v212
	v_pk_add_f32 v[12:13], v[12:13], v[240:241]
	v_pk_add_f32 v[10:11], v[10:11], v[212:213]
	v_lshlrev_b32_e32 v226, 16, v215
	v_and_b32_e32 v227, 0xffff0000, v215
	v_and_b32_e32 v215, 0xffff0000, v214
	v_lshlrev_b32_e32 v214, 16, v214
	v_pk_add_f32 v[8:9], v[8:9], v[226:227]
	v_pk_add_f32 v[6:7], v[6:7], v[214:215]
	v_lshlrev_b32_e32 v240, 16, v217
	v_and_b32_e32 v241, 0xffff0000, v217
	v_and_b32_e32 v217, 0xffff0000, v216
	v_lshlrev_b32_e32 v216, 16, v216
	v_pk_add_f32 v[4:5], v[4:5], v[240:241]
	v_pk_add_f32 v[2:3], v[2:3], v[216:217]
	v_cvt_pk_bf16_f32 v14, v14, v15
	v_cvt_pk_bf16_f32 v15, v16, v17
	v_cvt_pk_bf16_f32 v10, v10, v11
	v_cvt_pk_bf16_f32 v11, v12, v13
	v_cvt_pk_bf16_f32 v6, v6, v7
	v_cvt_pk_bf16_f32 v7, v8, v9
	v_cvt_pk_bf16_f32 v2, v2, v3
	v_cvt_pk_bf16_f32 v3, v4, v5
	ds_bpermute_b32 v210, v244, v14
	ds_bpermute_b32 v211, v244, v15
	ds_bpermute_b32 v212, v244, v10
	ds_bpermute_b32 v213, v244, v11
	ds_bpermute_b32 v214, v245, v14
	ds_bpermute_b32 v215, v245, v15
	ds_bpermute_b32 v216, v245, v10
	ds_bpermute_b32 v217, v245, v11
	s_waitcnt lgkmcnt(0)
	v_cndmask_b32_e64 v210, v210, v212, s[98:99]
	v_cndmask_b32_e64 v211, v211, v213, s[98:99]
	v_add_u32_e32 v212, 0x58000, v246
	global_store_dwordx2 v212, v[210:211], s[8:9]
	v_cndmask_b32_e64 v214, v214, v216, s[98:99]
	v_cndmask_b32_e64 v215, v215, v217, s[98:99]
	v_add_u32_e32 v216, 0x5c000, v246
	global_store_dwordx2 v216, v[214:215], s[8:9]
	ds_bpermute_b32 v210, v244, v6
	ds_bpermute_b32 v211, v244, v7
	ds_bpermute_b32 v212, v244, v2
	ds_bpermute_b32 v213, v244, v3
	ds_bpermute_b32 v214, v245, v6
	ds_bpermute_b32 v215, v245, v7
	ds_bpermute_b32 v216, v245, v2
	ds_bpermute_b32 v217, v245, v3
	s_waitcnt lgkmcnt(0)
	v_cndmask_b32_e64 v210, v210, v212, s[98:99]
	v_cndmask_b32_e64 v211, v211, v213, s[98:99]
	v_add_u32_e32 v212, 0x58000, v246
	global_store_dwordx2 v212, v[210:211], s[8:9] offset:256
	v_cndmask_b32_e64 v214, v214, v216, s[98:99]
	v_cndmask_b32_e64 v215, v215, v217, s[98:99]
	v_add_u32_e32 v216, 0x5c000, v246
	global_store_dwordx2 v216, v[214:215], s[8:9] offset:256
	s_cbranch_vccz .LBB0_1522
	s_waitcnt vmcnt(0)
	s_cmpk_gt_u32 s3, 0xff
	s_cbranch_scc1 .LBB0_1527
	s_barrier
